# P3 pooling pre-phase rewritten by hand: 16 consecutive tokens per thread, 31 window rows loaded once, rows unpacked once per half and accumulated into 8 outputs at a time in the original order
# speedup vs baseline: 1.0138x; 1.0138x over previous
; __global__ void __launch_bounds__(512, 2) hybrid_fwd(Args args) {
;     ...
;             for (int it = tid; it < 256 * 32; it += 512) {
;                 const int t = pu.pm * 256 + (it >> 5), cg8 = pu.pn * 32 + (it & 31), tl = t & 8191, w = 2 << (cg8 >> 4);
;                 const bf16_t* xp = XP + (size_t)t * 512 + cg8 * 8;
;                 float sum[8];
; #pragma unroll
;                 for (int e = 0; e < 8; ++e) sum[e] = 0.f;
;                 u32x4 x0 = (u32x4){0u, 0u, 0u, 0u};
; #pragma unroll
;                 for (int j = 0; j < 16; ++j) {
;                     if (j < w && tl - j >= 0) {
;                         const u32x4 v = *(const u32x4*)(xp - (size_t)j * 512);
;                         if (j == 0) x0 = v;
; #pragma unroll
;                         for (int e = 0; e < 4; ++e) { sum[2 * e] += __builtin_bit_cast(float, v[e] << 16); sum[2 * e + 1] += __builtin_bit_cast(float, v[e] & 0xffff0000u); }
;                     }
;                 }
.LBB0_368:
	s_and_saveexec_b64 s[52:53], s[6:7]
	s_cbranch_execz .LBB0_359
	v_lshl_or_b32 v0, s64, 5, v27
	v_ashrrev_i32_e32 v2, 4, v0
	v_lshlrev_b32_e32 v0, 3, v0
	v_ashrrev_i32_e32 v1, 31, v0
	v_lshlrev_b32_e64 v28, v2, 2
	v_lshlrev_b64 v[0:1], 1, v[0:1]
	v_cmp_gt_i32_e32 vcc, 2, v28
	v_cmp_gt_i32_e64 s[10:11], 3, v28
	v_cmp_gt_i32_e64 s[12:13], 4, v28
	v_cmp_gt_i32_e64 s[14:15], 5, v28
	v_cmp_gt_i32_e64 s[16:17], 6, v28
	v_cmp_gt_i32_e64 s[18:19], 7, v28
	v_cmp_gt_i32_e64 s[20:21], 8, v28
	v_cmp_gt_i32_e64 s[22:23], 9, v28
	v_cmp_gt_i32_e64 s[24:25], 10, v28
	v_cmp_gt_i32_e64 s[26:27], 11, v28
	v_cmp_gt_i32_e64 s[28:29], 12, v28
	v_cmp_gt_i32_e64 s[30:31], 13, v28
	v_cmp_gt_i32_e64 s[34:35], 14, v28
	v_cmp_gt_i32_e64 s[36:37], 15, v28
	v_cmp_gt_i32_e64 s[38:39], 16, v28
	s_lshl_b32 s66, s65, 8
	v_lshl_add_u64 v[8:9], s[50:51], 0, v[0:1]
	v_cmp_lt_i32_e64 s[8:9], 0, v28
	v_lshl_add_u64 v[10:11], s[42:43], 0, v[0:1]
	s_mov_b64 s[54:55], 0
	s_xor_b64 s[56:57], vcc, -1
	s_xor_b64 s[10:11], s[10:11], -1
	s_xor_b64 s[12:13], s[12:13], -1
	s_xor_b64 s[14:15], s[14:15], -1
	s_xor_b64 s[16:17], s[16:17], -1
	s_xor_b64 s[18:19], s[18:19], -1
	s_xor_b64 s[20:21], s[20:21], -1
	s_xor_b64 s[22:23], s[22:23], -1
	s_xor_b64 s[24:25], s[24:25], -1
	s_xor_b64 s[26:27], s[26:27], -1
	s_xor_b64 s[28:29], s[28:29], -1
	s_xor_b64 s[30:31], s[30:31], -1
	s_xor_b64 s[34:35], s[34:35], -1
	s_xor_b64 s[36:37], s[36:37], -1
	s_xor_b64 s[38:39], s[38:39], -1
	v_mov_b32_e32 v29, v26
	v_lshrrev_b32_e32 v30, 5, v26
	v_lshl_add_u32 v30, v30, 4, s66
	v_ashrrev_i32_e32 v31, 31, v30
	v_lshlrev_b64 v[32:33], 10, v[30:31]
	v_lshl_add_u64 v[22:23], v[8:9], 0, v[32:33]
	v_lshl_add_u64 v[238:239], v[10:11], 0, v[32:33]
	v_and_b32_e32 v31, 0x1fff, v30
	v_add_co_u32_e32 v32, vcc, 0xffffc000, v22
	s_nop 1
	v_addc_co_u32_e32 v33, vcc, -1, v23, vcc
	global_load_dwordx4 v[40:43], v[32:33], off offset:1024
	global_load_dwordx4 v[44:47], v[32:33], off offset:2048
	global_load_dwordx4 v[48:51], v[32:33], off offset:3072
	v_add_co_u32_e32 v32, vcc, 0xffffd000, v22
	s_nop 1
	v_addc_co_u32_e32 v33, vcc, -1, v23, vcc
	global_load_dwordx4 v[52:55], v[32:33], off
	global_load_dwordx4 v[56:59], v[32:33], off offset:1024
	global_load_dwordx4 v[60:63], v[32:33], off offset:2048
	global_load_dwordx4 v[64:67], v[32:33], off offset:3072
	v_add_co_u32_e32 v32, vcc, 0xffffe000, v22
	s_nop 1
	v_addc_co_u32_e32 v33, vcc, -1, v23, vcc
	global_load_dwordx4 v[68:71], v[32:33], off
	global_load_dwordx4 v[72:75], v[32:33], off offset:1024
	global_load_dwordx4 v[76:79], v[32:33], off offset:2048
	global_load_dwordx4 v[80:83], v[32:33], off offset:3072
	v_add_co_u32_e32 v32, vcc, 0xfffff000, v22
	s_nop 1
	v_addc_co_u32_e32 v33, vcc, -1, v23, vcc
	global_load_dwordx4 v[84:87], v[32:33], off
	global_load_dwordx4 v[88:91], v[32:33], off offset:1024
	global_load_dwordx4 v[92:95], v[32:33], off offset:2048
	global_load_dwordx4 v[96:99], v[32:33], off offset:3072
	global_load_dwordx4 v[100:103], v[22:23], off
	global_load_dwordx4 v[104:107], v[22:23], off offset:1024
	global_load_dwordx4 v[108:111], v[22:23], off offset:2048
	global_load_dwordx4 v[112:115], v[22:23], off offset:3072
	v_add_co_u32_e32 v32, vcc, 0x1000, v22
	s_nop 1
	v_addc_co_u32_e32 v33, vcc, 0, v23, vcc
	global_load_dwordx4 v[116:119], v[32:33], off
	global_load_dwordx4 v[120:123], v[32:33], off offset:1024
	global_load_dwordx4 v[124:127], v[32:33], off offset:2048
	global_load_dwordx4 v[128:131], v[32:33], off offset:3072
	v_add_co_u32_e32 v32, vcc, 0x2000, v22
	s_nop 1
	v_addc_co_u32_e32 v33, vcc, 0, v23, vcc
	global_load_dwordx4 v[132:135], v[32:33], off
	global_load_dwordx4 v[136:139], v[32:33], off offset:1024
	global_load_dwordx4 v[140:143], v[32:33], off offset:2048
	global_load_dwordx4 v[144:147], v[32:33], off offset:3072
	v_add_co_u32_e32 v32, vcc, 0x3000, v22
	s_nop 1
	v_addc_co_u32_e32 v33, vcc, 0, v23, vcc
	global_load_dwordx4 v[148:151], v[32:33], off
	global_load_dwordx4 v[152:155], v[32:33], off offset:1024
	global_load_dwordx4 v[156:159], v[32:33], off offset:2048
	global_load_dwordx4 v[160:163], v[32:33], off offset:3072
	s_waitcnt vmcnt(0)
	v_cmp_eq_u32_e32 vcc, 0, v31
	s_and_saveexec_b64 s[58:59], vcc
	s_cbranch_execz .Lp3d_nz
	v_mov_b32_e32 v40, 0
	v_mov_b32_e32 v41, 0
	v_mov_b32_e32 v42, 0
	v_mov_b32_e32 v43, 0
	v_mov_b32_e32 v44, 0
	v_mov_b32_e32 v45, 0
	v_mov_b32_e32 v46, 0
	v_mov_b32_e32 v47, 0
	v_mov_b32_e32 v48, 0
	v_mov_b32_e32 v49, 0
	v_mov_b32_e32 v50, 0
	v_mov_b32_e32 v51, 0
	v_mov_b32_e32 v52, 0
	v_mov_b32_e32 v53, 0
	v_mov_b32_e32 v54, 0
	v_mov_b32_e32 v55, 0
	v_mov_b32_e32 v56, 0
	v_mov_b32_e32 v57, 0
	v_mov_b32_e32 v58, 0
	v_mov_b32_e32 v59, 0
	v_mov_b32_e32 v60, 0
	v_mov_b32_e32 v61, 0
	v_mov_b32_e32 v62, 0
	v_mov_b32_e32 v63, 0
	v_mov_b32_e32 v64, 0
	v_mov_b32_e32 v65, 0
	v_mov_b32_e32 v66, 0
	v_mov_b32_e32 v67, 0
	v_mov_b32_e32 v68, 0
	v_mov_b32_e32 v69, 0
	v_mov_b32_e32 v70, 0
	v_mov_b32_e32 v71, 0
	v_mov_b32_e32 v72, 0
	v_mov_b32_e32 v73, 0
	v_mov_b32_e32 v74, 0
	v_mov_b32_e32 v75, 0
	v_mov_b32_e32 v76, 0
	v_mov_b32_e32 v77, 0
	v_mov_b32_e32 v78, 0
	v_mov_b32_e32 v79, 0
	v_mov_b32_e32 v80, 0
	v_mov_b32_e32 v81, 0
	v_mov_b32_e32 v82, 0
	v_mov_b32_e32 v83, 0
	v_mov_b32_e32 v84, 0
	v_mov_b32_e32 v85, 0
	v_mov_b32_e32 v86, 0
	v_mov_b32_e32 v87, 0
	v_mov_b32_e32 v88, 0
	v_mov_b32_e32 v89, 0
	v_mov_b32_e32 v90, 0
	v_mov_b32_e32 v91, 0
	v_mov_b32_e32 v92, 0
	v_mov_b32_e32 v93, 0
	v_mov_b32_e32 v94, 0
	v_mov_b32_e32 v95, 0
	v_mov_b32_e32 v96, 0
	v_mov_b32_e32 v97, 0
	v_mov_b32_e32 v98, 0
	v_mov_b32_e32 v99, 0
; __global__ void __launch_bounds__(512, 2) hybrid_fwd(Args args) {
;     ...
;                 float sum[8];
; #pragma unroll
;                 for (int e = 0; e < 8; ++e) sum[e] = 0.f;
;                 u32x4 x0 = (u32x4){0u, 0u, 0u, 0u};
; #pragma unroll
;                 for (int j = 0; j < 16; ++j) {
;                     if (j < w && tl - j >= 0) {
;                         const u32x4 v = *(const u32x4*)(xp - (size_t)j * 512);
;                         if (j == 0) x0 = v;
; #pragma unroll
;                         for (int e = 0; e < 4; ++e) { sum[2 * e] += __builtin_bit_cast(float, v[e] << 16); sum[2 * e + 1] += __builtin_bit_cast(float, v[e] & 0xffff0000u); }
;                     }
;                 }
.Lp3d_nz:
	s_or_b64 exec, exec, s[58:59]
	v_mov_b32_e32 v164, 0
	v_mov_b32_e32 v165, 0
	v_mov_b32_e32 v166, 0
	v_mov_b32_e32 v167, 0
	v_mov_b32_e32 v168, 0
	v_mov_b32_e32 v169, 0
	v_mov_b32_e32 v170, 0
	v_mov_b32_e32 v171, 0
	v_mov_b32_e32 v172, 0
	v_mov_b32_e32 v173, 0
	v_mov_b32_e32 v174, 0
	v_mov_b32_e32 v175, 0
	v_mov_b32_e32 v176, 0
	v_mov_b32_e32 v177, 0
	v_mov_b32_e32 v178, 0
	v_mov_b32_e32 v179, 0
	v_mov_b32_e32 v180, 0
	v_mov_b32_e32 v181, 0
	v_mov_b32_e32 v182, 0
	v_mov_b32_e32 v183, 0
	v_mov_b32_e32 v184, 0
	v_mov_b32_e32 v185, 0
	v_mov_b32_e32 v186, 0
	v_mov_b32_e32 v187, 0
	v_mov_b32_e32 v188, 0
	v_mov_b32_e32 v189, 0
	v_mov_b32_e32 v190, 0
	v_mov_b32_e32 v191, 0
	v_mov_b32_e32 v192, 0
	v_mov_b32_e32 v193, 0
	v_mov_b32_e32 v194, 0
	v_mov_b32_e32 v195, 0
	v_mov_b32_e32 v196, 0
	v_mov_b32_e32 v197, 0
	v_mov_b32_e32 v198, 0
	v_mov_b32_e32 v199, 0
	v_mov_b32_e32 v200, 0
	v_mov_b32_e32 v201, 0
	v_mov_b32_e32 v202, 0
	v_mov_b32_e32 v203, 0
	v_mov_b32_e32 v204, 0
	v_mov_b32_e32 v205, 0
	v_mov_b32_e32 v206, 0
	v_mov_b32_e32 v207, 0
	v_mov_b32_e32 v208, 0
	v_mov_b32_e32 v209, 0
	v_mov_b32_e32 v210, 0
	v_mov_b32_e32 v211, 0
	v_mov_b32_e32 v212, 0
	v_mov_b32_e32 v213, 0
	v_mov_b32_e32 v214, 0
	v_mov_b32_e32 v215, 0
	v_mov_b32_e32 v216, 0
	v_mov_b32_e32 v217, 0
	v_mov_b32_e32 v218, 0
	v_mov_b32_e32 v219, 0
	v_mov_b32_e32 v222, 0
	v_mov_b32_e32 v223, 0
	v_mov_b32_e32 v224, 0
	v_mov_b32_e32 v225, 0
	v_mov_b32_e32 v226, 0
	v_mov_b32_e32 v227, 0
	v_mov_b32_e32 v228, 0
	v_mov_b32_e32 v229, 0
	v_lshlrev_b32_e32 v230, 16, v128
	v_and_b32_e32 v231, 0xffff0000, v128
	v_lshlrev_b32_e32 v232, 16, v129
	v_and_b32_e32 v233, 0xffff0000, v129
	v_lshlrev_b32_e32 v234, 16, v130
	v_and_b32_e32 v235, 0xffff0000, v130
	v_lshlrev_b32_e32 v236, 16, v131
	v_and_b32_e32 v237, 0xffff0000, v131
	v_pk_add_f32 v[222:223], v[222:223], v[230:231]
	v_pk_add_f32 v[224:225], v[224:225], v[232:233]
	v_pk_add_f32 v[226:227], v[226:227], v[234:235]
	v_pk_add_f32 v[228:229], v[228:229], v[236:237]
	v_lshlrev_b32_e32 v230, 16, v124
	v_and_b32_e32 v231, 0xffff0000, v124
	v_lshlrev_b32_e32 v232, 16, v125
	v_and_b32_e32 v233, 0xffff0000, v125
	v_lshlrev_b32_e32 v234, 16, v126
	v_and_b32_e32 v235, 0xffff0000, v126
	v_lshlrev_b32_e32 v236, 16, v127
	v_and_b32_e32 v237, 0xffff0000, v127
	v_pk_add_f32 v[212:213], v[212:213], v[230:231]
	v_pk_add_f32 v[214:215], v[214:215], v[232:233]
	v_pk_add_f32 v[216:217], v[216:217], v[234:235]
	v_pk_add_f32 v[218:219], v[218:219], v[236:237]
	v_pk_add_f32 v[222:223], v[222:223], v[230:231]
	v_pk_add_f32 v[224:225], v[224:225], v[232:233]
	v_pk_add_f32 v[226:227], v[226:227], v[234:235]
	v_pk_add_f32 v[228:229], v[228:229], v[236:237]
	v_lshlrev_b32_e32 v230, 16, v120
	v_and_b32_e32 v231, 0xffff0000, v120
	v_lshlrev_b32_e32 v232, 16, v121
	v_and_b32_e32 v233, 0xffff0000, v121
	v_lshlrev_b32_e32 v234, 16, v122
	v_and_b32_e32 v235, 0xffff0000, v122
	v_lshlrev_b32_e32 v236, 16, v123
	v_and_b32_e32 v237, 0xffff0000, v123
	v_pk_add_f32 v[204:205], v[204:205], v[230:231]
	v_pk_add_f32 v[206:207], v[206:207], v[232:233]
	v_pk_add_f32 v[208:209], v[208:209], v[234:235]
	v_pk_add_f32 v[210:211], v[210:211], v[236:237]
	v_pk_add_f32 v[212:213], v[212:213], v[230:231]
	v_pk_add_f32 v[214:215], v[214:215], v[232:233]
	v_pk_add_f32 v[216:217], v[216:217], v[234:235]
	v_pk_add_f32 v[218:219], v[218:219], v[236:237]
	s_and_saveexec_b64 s[58:59], s[10:11]
	s_cbranch_execz .Lp3d_s1
	v_pk_add_f32 v[222:223], v[222:223], v[230:231]
	v_pk_add_f32 v[224:225], v[224:225], v[232:233]
	v_pk_add_f32 v[226:227], v[226:227], v[234:235]
	v_pk_add_f32 v[228:229], v[228:229], v[236:237]
.Lp3d_s1:
	s_or_b64 exec, exec, s[58:59]
	v_lshlrev_b32_e32 v230, 16, v116
	v_and_b32_e32 v231, 0xffff0000, v116
	v_lshlrev_b32_e32 v232, 16, v117
	v_and_b32_e32 v233, 0xffff0000, v117
	v_lshlrev_b32_e32 v234, 16, v118
	v_and_b32_e32 v235, 0xffff0000, v118
	v_lshlrev_b32_e32 v236, 16, v119
	v_and_b32_e32 v237, 0xffff0000, v119
	v_pk_add_f32 v[196:197], v[196:197], v[230:231]
	v_pk_add_f32 v[198:199], v[198:199], v[232:233]
	v_pk_add_f32 v[200:201], v[200:201], v[234:235]
	v_pk_add_f32 v[202:203], v[202:203], v[236:237]
	v_pk_add_f32 v[204:205], v[204:205], v[230:231]
	v_pk_add_f32 v[206:207], v[206:207], v[232:233]
	v_pk_add_f32 v[208:209], v[208:209], v[234:235]
	v_pk_add_f32 v[210:211], v[210:211], v[236:237]
	s_and_saveexec_b64 s[58:59], s[10:11]
	s_cbranch_execz .Lp3d_s2
	v_pk_add_f32 v[212:213], v[212:213], v[230:231]
	v_pk_add_f32 v[214:215], v[214:215], v[232:233]
	v_pk_add_f32 v[216:217], v[216:217], v[234:235]
	v_pk_add_f32 v[218:219], v[218:219], v[236:237]
	v_pk_add_f32 v[222:223], v[222:223], v[230:231]
	v_pk_add_f32 v[224:225], v[224:225], v[232:233]
	v_pk_add_f32 v[226:227], v[226:227], v[234:235]
	v_pk_add_f32 v[228:229], v[228:229], v[236:237]
.Lp3d_s2:
	s_or_b64 exec, exec, s[58:59]
	v_lshlrev_b32_e32 v230, 16, v112
	v_and_b32_e32 v231, 0xffff0000, v112
	v_lshlrev_b32_e32 v232, 16, v113
	v_and_b32_e32 v233, 0xffff0000, v113
	v_lshlrev_b32_e32 v234, 16, v114
	v_and_b32_e32 v235, 0xffff0000, v114
	v_lshlrev_b32_e32 v236, 16, v115
	v_and_b32_e32 v237, 0xffff0000, v115
	v_pk_add_f32 v[188:189], v[188:189], v[230:231]
	v_pk_add_f32 v[190:191], v[190:191], v[232:233]
	v_pk_add_f32 v[192:193], v[192:193], v[234:235]
	v_pk_add_f32 v[194:195], v[194:195], v[236:237]
	v_pk_add_f32 v[196:197], v[196:197], v[230:231]
	v_pk_add_f32 v[198:199], v[198:199], v[232:233]
	v_pk_add_f32 v[200:201], v[200:201], v[234:235]
	v_pk_add_f32 v[202:203], v[202:203], v[236:237]
	s_and_saveexec_b64 s[58:59], s[10:11]
	s_cbranch_execz .Lp3d_s3
	v_pk_add_f32 v[204:205], v[204:205], v[230:231]
	v_pk_add_f32 v[206:207], v[206:207], v[232:233]
	v_pk_add_f32 v[208:209], v[208:209], v[234:235]
	v_pk_add_f32 v[210:211], v[210:211], v[236:237]
	v_pk_add_f32 v[212:213], v[212:213], v[230:231]
	v_pk_add_f32 v[214:215], v[214:215], v[232:233]
	v_pk_add_f32 v[216:217], v[216:217], v[234:235]
	v_pk_add_f32 v[218:219], v[218:219], v[236:237]
; __global__ void __launch_bounds__(512, 2) hybrid_fwd(Args args) {
;     ...
;                 for (int j = 0; j < 16; ++j) {
;                     if (j < w && tl - j >= 0) {
;                         const u32x4 v = *(const u32x4*)(xp - (size_t)j * 512);
;                         if (j == 0) x0 = v;
; #pragma unroll
;                         for (int e = 0; e < 4; ++e) { sum[2 * e] += __builtin_bit_cast(float, v[e] << 16); sum[2 * e + 1] += __builtin_bit_cast(float, v[e] & 0xffff0000u); }
;                     }
;                 }
.Lp3d_s3:
	s_or_b64 exec, exec, s[58:59]
	s_and_saveexec_b64 s[58:59], s[14:15]
	s_cbranch_execz .Lp3d_s4
	v_pk_add_f32 v[222:223], v[222:223], v[230:231]
	v_pk_add_f32 v[224:225], v[224:225], v[232:233]
	v_pk_add_f32 v[226:227], v[226:227], v[234:235]
	v_pk_add_f32 v[228:229], v[228:229], v[236:237]
.Lp3d_s4:
	s_or_b64 exec, exec, s[58:59]
	v_lshlrev_b32_e32 v230, 16, v108
	v_and_b32_e32 v231, 0xffff0000, v108
	v_lshlrev_b32_e32 v232, 16, v109
	v_and_b32_e32 v233, 0xffff0000, v109
	v_lshlrev_b32_e32 v234, 16, v110
	v_and_b32_e32 v235, 0xffff0000, v110
	v_lshlrev_b32_e32 v236, 16, v111
	v_and_b32_e32 v237, 0xffff0000, v111
	v_pk_add_f32 v[180:181], v[180:181], v[230:231]
	v_pk_add_f32 v[182:183], v[182:183], v[232:233]
	v_pk_add_f32 v[184:185], v[184:185], v[234:235]
	v_pk_add_f32 v[186:187], v[186:187], v[236:237]
	v_pk_add_f32 v[188:189], v[188:189], v[230:231]
	v_pk_add_f32 v[190:191], v[190:191], v[232:233]
	v_pk_add_f32 v[192:193], v[192:193], v[234:235]
	v_pk_add_f32 v[194:195], v[194:195], v[236:237]
	s_and_saveexec_b64 s[58:59], s[10:11]
	s_cbranch_execz .Lp3d_s5
	v_pk_add_f32 v[196:197], v[196:197], v[230:231]
	v_pk_add_f32 v[198:199], v[198:199], v[232:233]
	v_pk_add_f32 v[200:201], v[200:201], v[234:235]
	v_pk_add_f32 v[202:203], v[202:203], v[236:237]
	v_pk_add_f32 v[204:205], v[204:205], v[230:231]
	v_pk_add_f32 v[206:207], v[206:207], v[232:233]
	v_pk_add_f32 v[208:209], v[208:209], v[234:235]
	v_pk_add_f32 v[210:211], v[210:211], v[236:237]
.Lp3d_s5:
	s_or_b64 exec, exec, s[58:59]
	s_and_saveexec_b64 s[58:59], s[14:15]
	s_cbranch_execz .Lp3d_s6
	v_pk_add_f32 v[212:213], v[212:213], v[230:231]
	v_pk_add_f32 v[214:215], v[214:215], v[232:233]
	v_pk_add_f32 v[216:217], v[216:217], v[234:235]
	v_pk_add_f32 v[218:219], v[218:219], v[236:237]
	v_pk_add_f32 v[222:223], v[222:223], v[230:231]
	v_pk_add_f32 v[224:225], v[224:225], v[232:233]
	v_pk_add_f32 v[226:227], v[226:227], v[234:235]
	v_pk_add_f32 v[228:229], v[228:229], v[236:237]
.Lp3d_s6:
	s_or_b64 exec, exec, s[58:59]
	v_lshlrev_b32_e32 v230, 16, v104
	v_and_b32_e32 v231, 0xffff0000, v104
	v_lshlrev_b32_e32 v232, 16, v105
	v_and_b32_e32 v233, 0xffff0000, v105
	v_lshlrev_b32_e32 v234, 16, v106
	v_and_b32_e32 v235, 0xffff0000, v106
	v_lshlrev_b32_e32 v236, 16, v107
	v_and_b32_e32 v237, 0xffff0000, v107
	v_pk_add_f32 v[172:173], v[172:173], v[230:231]
	v_pk_add_f32 v[174:175], v[174:175], v[232:233]
	v_pk_add_f32 v[176:177], v[176:177], v[234:235]
	v_pk_add_f32 v[178:179], v[178:179], v[236:237]
	v_pk_add_f32 v[180:181], v[180:181], v[230:231]
	v_pk_add_f32 v[182:183], v[182:183], v[232:233]
	v_pk_add_f32 v[184:185], v[184:185], v[234:235]
	v_pk_add_f32 v[186:187], v[186:187], v[236:237]
	s_and_saveexec_b64 s[58:59], s[10:11]
	s_cbranch_execz .Lp3d_s7
	v_pk_add_f32 v[188:189], v[188:189], v[230:231]
	v_pk_add_f32 v[190:191], v[190:191], v[232:233]
	v_pk_add_f32 v[192:193], v[192:193], v[234:235]
	v_pk_add_f32 v[194:195], v[194:195], v[236:237]
	v_pk_add_f32 v[196:197], v[196:197], v[230:231]
	v_pk_add_f32 v[198:199], v[198:199], v[232:233]
	v_pk_add_f32 v[200:201], v[200:201], v[234:235]
	v_pk_add_f32 v[202:203], v[202:203], v[236:237]
.Lp3d_s7:
	s_or_b64 exec, exec, s[58:59]
	s_and_saveexec_b64 s[58:59], s[14:15]
	s_cbranch_execz .Lp3d_s8
	v_pk_add_f32 v[204:205], v[204:205], v[230:231]
	v_pk_add_f32 v[206:207], v[206:207], v[232:233]
	v_pk_add_f32 v[208:209], v[208:209], v[234:235]
	v_pk_add_f32 v[210:211], v[210:211], v[236:237]
	v_pk_add_f32 v[212:213], v[212:213], v[230:231]
	v_pk_add_f32 v[214:215], v[214:215], v[232:233]
	v_pk_add_f32 v[216:217], v[216:217], v[234:235]
	v_pk_add_f32 v[218:219], v[218:219], v[236:237]
	v_pk_add_f32 v[222:223], v[222:223], v[230:231]
	v_pk_add_f32 v[224:225], v[224:225], v[232:233]
	v_pk_add_f32 v[226:227], v[226:227], v[234:235]
	v_pk_add_f32 v[228:229], v[228:229], v[236:237]
.Lp3d_s8:
	s_or_b64 exec, exec, s[58:59]
	v_lshlrev_b32_e32 v230, 16, v100
	v_and_b32_e32 v231, 0xffff0000, v100
	v_lshlrev_b32_e32 v232, 16, v101
	v_and_b32_e32 v233, 0xffff0000, v101
	v_lshlrev_b32_e32 v234, 16, v102
	v_and_b32_e32 v235, 0xffff0000, v102
	v_lshlrev_b32_e32 v236, 16, v103
	v_and_b32_e32 v237, 0xffff0000, v103
	v_pk_add_f32 v[164:165], v[164:165], v[230:231]
	v_pk_add_f32 v[166:167], v[166:167], v[232:233]
	v_pk_add_f32 v[168:169], v[168:169], v[234:235]
	v_pk_add_f32 v[170:171], v[170:171], v[236:237]
	v_pk_add_f32 v[172:173], v[172:173], v[230:231]
	v_pk_add_f32 v[174:175], v[174:175], v[232:233]
	v_pk_add_f32 v[176:177], v[176:177], v[234:235]
	v_pk_add_f32 v[178:179], v[178:179], v[236:237]
	s_and_saveexec_b64 s[58:59], s[10:11]
	s_cbranch_execz .Lp3d_s9
	v_pk_add_f32 v[180:181], v[180:181], v[230:231]
	v_pk_add_f32 v[182:183], v[182:183], v[232:233]
	v_pk_add_f32 v[184:185], v[184:185], v[234:235]
	v_pk_add_f32 v[186:187], v[186:187], v[236:237]
	v_pk_add_f32 v[188:189], v[188:189], v[230:231]
	v_pk_add_f32 v[190:191], v[190:191], v[232:233]
	v_pk_add_f32 v[192:193], v[192:193], v[234:235]
	v_pk_add_f32 v[194:195], v[194:195], v[236:237]
.Lp3d_s9:
	s_or_b64 exec, exec, s[58:59]
	s_and_saveexec_b64 s[58:59], s[14:15]
	s_cbranch_execz .Lp3d_s10
	v_pk_add_f32 v[196:197], v[196:197], v[230:231]
	v_pk_add_f32 v[198:199], v[198:199], v[232:233]
	v_pk_add_f32 v[200:201], v[200:201], v[234:235]
	v_pk_add_f32 v[202:203], v[202:203], v[236:237]
	v_pk_add_f32 v[204:205], v[204:205], v[230:231]
	v_pk_add_f32 v[206:207], v[206:207], v[232:233]
	v_pk_add_f32 v[208:209], v[208:209], v[234:235]
	v_pk_add_f32 v[210:211], v[210:211], v[236:237]
	v_pk_add_f32 v[212:213], v[212:213], v[230:231]
	v_pk_add_f32 v[214:215], v[214:215], v[232:233]
	v_pk_add_f32 v[216:217], v[216:217], v[234:235]
	v_pk_add_f32 v[218:219], v[218:219], v[236:237]
	v_pk_add_f32 v[222:223], v[222:223], v[230:231]
	v_pk_add_f32 v[224:225], v[224:225], v[232:233]
	v_pk_add_f32 v[226:227], v[226:227], v[234:235]
	v_pk_add_f32 v[228:229], v[228:229], v[236:237]
; __global__ void __launch_bounds__(512, 2) hybrid_fwd(Args args) {
;     ...
;                 for (int j = 0; j < 16; ++j) {
;                     if (j < w && tl - j >= 0) {
;                         const u32x4 v = *(const u32x4*)(xp - (size_t)j * 512);
;                         if (j == 0) x0 = v;
; #pragma unroll
;                         for (int e = 0; e < 4; ++e) { sum[2 * e] += __builtin_bit_cast(float, v[e] << 16); sum[2 * e + 1] += __builtin_bit_cast(float, v[e] & 0xffff0000u); }
;                     }
;                 }
.Lp3d_s10:
	s_or_b64 exec, exec, s[58:59]
	v_lshlrev_b32_e32 v230, 16, v96
	v_and_b32_e32 v231, 0xffff0000, v96
	v_lshlrev_b32_e32 v232, 16, v97
	v_and_b32_e32 v233, 0xffff0000, v97
	v_lshlrev_b32_e32 v234, 16, v98
	v_and_b32_e32 v235, 0xffff0000, v98
	v_lshlrev_b32_e32 v236, 16, v99
	v_and_b32_e32 v237, 0xffff0000, v99
	v_pk_add_f32 v[164:165], v[164:165], v[230:231]
	v_pk_add_f32 v[166:167], v[166:167], v[232:233]
	v_pk_add_f32 v[168:169], v[168:169], v[234:235]
	v_pk_add_f32 v[170:171], v[170:171], v[236:237]
	s_and_saveexec_b64 s[58:59], s[10:11]
	s_cbranch_execz .Lp3d_s11
	v_pk_add_f32 v[172:173], v[172:173], v[230:231]
	v_pk_add_f32 v[174:175], v[174:175], v[232:233]
	v_pk_add_f32 v[176:177], v[176:177], v[234:235]
	v_pk_add_f32 v[178:179], v[178:179], v[236:237]
	v_pk_add_f32 v[180:181], v[180:181], v[230:231]
	v_pk_add_f32 v[182:183], v[182:183], v[232:233]
	v_pk_add_f32 v[184:185], v[184:185], v[234:235]
	v_pk_add_f32 v[186:187], v[186:187], v[236:237]
.Lp3d_s11:
	s_or_b64 exec, exec, s[58:59]
	s_and_saveexec_b64 s[58:59], s[14:15]
	s_cbranch_execz .Lp3d_s12
	v_pk_add_f32 v[188:189], v[188:189], v[230:231]
	v_pk_add_f32 v[190:191], v[190:191], v[232:233]
	v_pk_add_f32 v[192:193], v[192:193], v[234:235]
	v_pk_add_f32 v[194:195], v[194:195], v[236:237]
	v_pk_add_f32 v[196:197], v[196:197], v[230:231]
	v_pk_add_f32 v[198:199], v[198:199], v[232:233]
	v_pk_add_f32 v[200:201], v[200:201], v[234:235]
	v_pk_add_f32 v[202:203], v[202:203], v[236:237]
	v_pk_add_f32 v[204:205], v[204:205], v[230:231]
	v_pk_add_f32 v[206:207], v[206:207], v[232:233]
	v_pk_add_f32 v[208:209], v[208:209], v[234:235]
	v_pk_add_f32 v[210:211], v[210:211], v[236:237]
	v_pk_add_f32 v[212:213], v[212:213], v[230:231]
	v_pk_add_f32 v[214:215], v[214:215], v[232:233]
	v_pk_add_f32 v[216:217], v[216:217], v[234:235]
	v_pk_add_f32 v[218:219], v[218:219], v[236:237]
.Lp3d_s12:
	s_or_b64 exec, exec, s[58:59]
	s_and_saveexec_b64 s[58:59], s[22:23]
	s_cbranch_execz .Lp3d_s13
	v_pk_add_f32 v[222:223], v[222:223], v[230:231]
	v_pk_add_f32 v[224:225], v[224:225], v[232:233]
	v_pk_add_f32 v[226:227], v[226:227], v[234:235]
	v_pk_add_f32 v[228:229], v[228:229], v[236:237]
.Lp3d_s13:
	s_or_b64 exec, exec, s[58:59]
	v_lshlrev_b32_e32 v230, 16, v92
	v_and_b32_e32 v231, 0xffff0000, v92
	v_lshlrev_b32_e32 v232, 16, v93
	v_and_b32_e32 v233, 0xffff0000, v93
	v_lshlrev_b32_e32 v234, 16, v94
	v_and_b32_e32 v235, 0xffff0000, v94
	v_lshlrev_b32_e32 v236, 16, v95
	v_and_b32_e32 v237, 0xffff0000, v95
	s_and_saveexec_b64 s[58:59], s[10:11]
	s_cbranch_execz .Lp3d_s14
	v_pk_add_f32 v[164:165], v[164:165], v[230:231]
	v_pk_add_f32 v[166:167], v[166:167], v[232:233]
	v_pk_add_f32 v[168:169], v[168:169], v[234:235]
	v_pk_add_f32 v[170:171], v[170:171], v[236:237]
	v_pk_add_f32 v[172:173], v[172:173], v[230:231]
	v_pk_add_f32 v[174:175], v[174:175], v[232:233]
	v_pk_add_f32 v[176:177], v[176:177], v[234:235]
	v_pk_add_f32 v[178:179], v[178:179], v[236:237]
.Lp3d_s14:
	s_or_b64 exec, exec, s[58:59]
	s_and_saveexec_b64 s[58:59], s[14:15]
	s_cbranch_execz .Lp3d_s15
	v_pk_add_f32 v[180:181], v[180:181], v[230:231]
	v_pk_add_f32 v[182:183], v[182:183], v[232:233]
	v_pk_add_f32 v[184:185], v[184:185], v[234:235]
	v_pk_add_f32 v[186:187], v[186:187], v[236:237]
	v_pk_add_f32 v[188:189], v[188:189], v[230:231]
	v_pk_add_f32 v[190:191], v[190:191], v[232:233]
	v_pk_add_f32 v[192:193], v[192:193], v[234:235]
	v_pk_add_f32 v[194:195], v[194:195], v[236:237]
	v_pk_add_f32 v[196:197], v[196:197], v[230:231]
	v_pk_add_f32 v[198:199], v[198:199], v[232:233]
	v_pk_add_f32 v[200:201], v[200:201], v[234:235]
	v_pk_add_f32 v[202:203], v[202:203], v[236:237]
	v_pk_add_f32 v[204:205], v[204:205], v[230:231]
	v_pk_add_f32 v[206:207], v[206:207], v[232:233]
	v_pk_add_f32 v[208:209], v[208:209], v[234:235]
	v_pk_add_f32 v[210:211], v[210:211], v[236:237]
.Lp3d_s15:
	s_or_b64 exec, exec, s[58:59]
	s_and_saveexec_b64 s[58:59], s[22:23]
	s_cbranch_execz .Lp3d_s16
	v_pk_add_f32 v[212:213], v[212:213], v[230:231]
	v_pk_add_f32 v[214:215], v[214:215], v[232:233]
	v_pk_add_f32 v[216:217], v[216:217], v[234:235]
	v_pk_add_f32 v[218:219], v[218:219], v[236:237]
	v_pk_add_f32 v[222:223], v[222:223], v[230:231]
	v_pk_add_f32 v[224:225], v[224:225], v[232:233]
	v_pk_add_f32 v[226:227], v[226:227], v[234:235]
	v_pk_add_f32 v[228:229], v[228:229], v[236:237]
.Lp3d_s16:
	s_or_b64 exec, exec, s[58:59]
	v_lshlrev_b32_e32 v230, 16, v88
	v_and_b32_e32 v231, 0xffff0000, v88
	v_lshlrev_b32_e32 v232, 16, v89
	v_and_b32_e32 v233, 0xffff0000, v89
	v_lshlrev_b32_e32 v234, 16, v90
	v_and_b32_e32 v235, 0xffff0000, v90
	v_lshlrev_b32_e32 v236, 16, v91
	v_and_b32_e32 v237, 0xffff0000, v91
	s_and_saveexec_b64 s[58:59], s[10:11]
	s_cbranch_execz .Lp3d_s17
	v_pk_add_f32 v[164:165], v[164:165], v[230:231]
	v_pk_add_f32 v[166:167], v[166:167], v[232:233]
	v_pk_add_f32 v[168:169], v[168:169], v[234:235]
	v_pk_add_f32 v[170:171], v[170:171], v[236:237]
.Lp3d_s17:
	s_or_b64 exec, exec, s[58:59]
	s_and_saveexec_b64 s[58:59], s[14:15]
	s_cbranch_execz .Lp3d_s18
	v_pk_add_f32 v[172:173], v[172:173], v[230:231]
	v_pk_add_f32 v[174:175], v[174:175], v[232:233]
	v_pk_add_f32 v[176:177], v[176:177], v[234:235]
	v_pk_add_f32 v[178:179], v[178:179], v[236:237]
	v_pk_add_f32 v[180:181], v[180:181], v[230:231]
	v_pk_add_f32 v[182:183], v[182:183], v[232:233]
	v_pk_add_f32 v[184:185], v[184:185], v[234:235]
	v_pk_add_f32 v[186:187], v[186:187], v[236:237]
	v_pk_add_f32 v[188:189], v[188:189], v[230:231]
	v_pk_add_f32 v[190:191], v[190:191], v[232:233]
	v_pk_add_f32 v[192:193], v[192:193], v[234:235]
	v_pk_add_f32 v[194:195], v[194:195], v[236:237]
	v_pk_add_f32 v[196:197], v[196:197], v[230:231]
	v_pk_add_f32 v[198:199], v[198:199], v[232:233]
	v_pk_add_f32 v[200:201], v[200:201], v[234:235]
	v_pk_add_f32 v[202:203], v[202:203], v[236:237]
; __global__ void __launch_bounds__(512, 2) hybrid_fwd(Args args) {
;     ...
;                 for (int j = 0; j < 16; ++j) {
;                     if (j < w && tl - j >= 0) {
;                         const u32x4 v = *(const u32x4*)(xp - (size_t)j * 512);
;                         if (j == 0) x0 = v;
; #pragma unroll
;                         for (int e = 0; e < 4; ++e) { sum[2 * e] += __builtin_bit_cast(float, v[e] << 16); sum[2 * e + 1] += __builtin_bit_cast(float, v[e] & 0xffff0000u); }
;                     }
;                 }
.Lp3d_s18:
	s_or_b64 exec, exec, s[58:59]
	s_and_saveexec_b64 s[58:59], s[22:23]
	s_cbranch_execz .Lp3d_s19
	v_pk_add_f32 v[204:205], v[204:205], v[230:231]
	v_pk_add_f32 v[206:207], v[206:207], v[232:233]
	v_pk_add_f32 v[208:209], v[208:209], v[234:235]
	v_pk_add_f32 v[210:211], v[210:211], v[236:237]
	v_pk_add_f32 v[212:213], v[212:213], v[230:231]
	v_pk_add_f32 v[214:215], v[214:215], v[232:233]
	v_pk_add_f32 v[216:217], v[216:217], v[234:235]
	v_pk_add_f32 v[218:219], v[218:219], v[236:237]
	v_pk_add_f32 v[222:223], v[222:223], v[230:231]
	v_pk_add_f32 v[224:225], v[224:225], v[232:233]
	v_pk_add_f32 v[226:227], v[226:227], v[234:235]
	v_pk_add_f32 v[228:229], v[228:229], v[236:237]
.Lp3d_s19:
	s_or_b64 exec, exec, s[58:59]
	v_lshlrev_b32_e32 v230, 16, v84
	v_and_b32_e32 v231, 0xffff0000, v84
	v_lshlrev_b32_e32 v232, 16, v85
	v_and_b32_e32 v233, 0xffff0000, v85
	v_lshlrev_b32_e32 v234, 16, v86
	v_and_b32_e32 v235, 0xffff0000, v86
	v_lshlrev_b32_e32 v236, 16, v87
	v_and_b32_e32 v237, 0xffff0000, v87
	s_and_saveexec_b64 s[58:59], s[14:15]
	s_cbranch_execz .Lp3d_s20
	v_pk_add_f32 v[164:165], v[164:165], v[230:231]
	v_pk_add_f32 v[166:167], v[166:167], v[232:233]
	v_pk_add_f32 v[168:169], v[168:169], v[234:235]
	v_pk_add_f32 v[170:171], v[170:171], v[236:237]
	v_pk_add_f32 v[172:173], v[172:173], v[230:231]
	v_pk_add_f32 v[174:175], v[174:175], v[232:233]
	v_pk_add_f32 v[176:177], v[176:177], v[234:235]
	v_pk_add_f32 v[178:179], v[178:179], v[236:237]
	v_pk_add_f32 v[180:181], v[180:181], v[230:231]
	v_pk_add_f32 v[182:183], v[182:183], v[232:233]
	v_pk_add_f32 v[184:185], v[184:185], v[234:235]
	v_pk_add_f32 v[186:187], v[186:187], v[236:237]
	v_pk_add_f32 v[188:189], v[188:189], v[230:231]
	v_pk_add_f32 v[190:191], v[190:191], v[232:233]
	v_pk_add_f32 v[192:193], v[192:193], v[234:235]
	v_pk_add_f32 v[194:195], v[194:195], v[236:237]
.Lp3d_s20:
	s_or_b64 exec, exec, s[58:59]
	s_and_saveexec_b64 s[58:59], s[22:23]
	s_cbranch_execz .Lp3d_s21
	v_pk_add_f32 v[196:197], v[196:197], v[230:231]
	v_pk_add_f32 v[198:199], v[198:199], v[232:233]
	v_pk_add_f32 v[200:201], v[200:201], v[234:235]
	v_pk_add_f32 v[202:203], v[202:203], v[236:237]
	v_pk_add_f32 v[204:205], v[204:205], v[230:231]
	v_pk_add_f32 v[206:207], v[206:207], v[232:233]
	v_pk_add_f32 v[208:209], v[208:209], v[234:235]
	v_pk_add_f32 v[210:211], v[210:211], v[236:237]
	v_pk_add_f32 v[212:213], v[212:213], v[230:231]
	v_pk_add_f32 v[214:215], v[214:215], v[232:233]
	v_pk_add_f32 v[216:217], v[216:217], v[234:235]
	v_pk_add_f32 v[218:219], v[218:219], v[236:237]
	v_pk_add_f32 v[222:223], v[222:223], v[230:231]
	v_pk_add_f32 v[224:225], v[224:225], v[232:233]
	v_pk_add_f32 v[226:227], v[226:227], v[234:235]
	v_pk_add_f32 v[228:229], v[228:229], v[236:237]
.Lp3d_s21:
	s_or_b64 exec, exec, s[58:59]
	v_lshlrev_b32_e32 v230, 16, v80
	v_and_b32_e32 v231, 0xffff0000, v80
	v_lshlrev_b32_e32 v232, 16, v81
	v_and_b32_e32 v233, 0xffff0000, v81
	v_lshlrev_b32_e32 v234, 16, v82
	v_and_b32_e32 v235, 0xffff0000, v82
	v_lshlrev_b32_e32 v236, 16, v83
	v_and_b32_e32 v237, 0xffff0000, v83
	s_and_saveexec_b64 s[58:59], s[14:15]
	s_cbranch_execz .Lp3d_s22
	v_pk_add_f32 v[164:165], v[164:165], v[230:231]
	v_pk_add_f32 v[166:167], v[166:167], v[232:233]
	v_pk_add_f32 v[168:169], v[168:169], v[234:235]
	v_pk_add_f32 v[170:171], v[170:171], v[236:237]
	v_pk_add_f32 v[172:173], v[172:173], v[230:231]
	v_pk_add_f32 v[174:175], v[174:175], v[232:233]
	v_pk_add_f32 v[176:177], v[176:177], v[234:235]
	v_pk_add_f32 v[178:179], v[178:179], v[236:237]
	v_pk_add_f32 v[180:181], v[180:181], v[230:231]
	v_pk_add_f32 v[182:183], v[182:183], v[232:233]
	v_pk_add_f32 v[184:185], v[184:185], v[234:235]
	v_pk_add_f32 v[186:187], v[186:187], v[236:237]
.Lp3d_s22:
	s_or_b64 exec, exec, s[58:59]
	s_and_saveexec_b64 s[58:59], s[22:23]
	s_cbranch_execz .Lp3d_s23
	v_pk_add_f32 v[188:189], v[188:189], v[230:231]
	v_pk_add_f32 v[190:191], v[190:191], v[232:233]
	v_pk_add_f32 v[192:193], v[192:193], v[234:235]
	v_pk_add_f32 v[194:195], v[194:195], v[236:237]
	v_pk_add_f32 v[196:197], v[196:197], v[230:231]
	v_pk_add_f32 v[198:199], v[198:199], v[232:233]
	v_pk_add_f32 v[200:201], v[200:201], v[234:235]
	v_pk_add_f32 v[202:203], v[202:203], v[236:237]
	v_pk_add_f32 v[204:205], v[204:205], v[230:231]
	v_pk_add_f32 v[206:207], v[206:207], v[232:233]
	v_pk_add_f32 v[208:209], v[208:209], v[234:235]
	v_pk_add_f32 v[210:211], v[210:211], v[236:237]
	v_pk_add_f32 v[212:213], v[212:213], v[230:231]
	v_pk_add_f32 v[214:215], v[214:215], v[232:233]
	v_pk_add_f32 v[216:217], v[216:217], v[234:235]
	v_pk_add_f32 v[218:219], v[218:219], v[236:237]
	v_pk_add_f32 v[222:223], v[222:223], v[230:231]
	v_pk_add_f32 v[224:225], v[224:225], v[232:233]
	v_pk_add_f32 v[226:227], v[226:227], v[234:235]
	v_pk_add_f32 v[228:229], v[228:229], v[236:237]
.Lp3d_s23:
	s_or_b64 exec, exec, s[58:59]
	v_lshlrev_b32_e32 v230, 16, v76
	v_and_b32_e32 v231, 0xffff0000, v76
	v_lshlrev_b32_e32 v232, 16, v77
	v_and_b32_e32 v233, 0xffff0000, v77
	v_lshlrev_b32_e32 v234, 16, v78
	v_and_b32_e32 v235, 0xffff0000, v78
	v_lshlrev_b32_e32 v236, 16, v79
	v_and_b32_e32 v237, 0xffff0000, v79
	s_and_saveexec_b64 s[58:59], s[14:15]
	s_cbranch_execz .Lp3d_s24
	v_pk_add_f32 v[164:165], v[164:165], v[230:231]
	v_pk_add_f32 v[166:167], v[166:167], v[232:233]
	v_pk_add_f32 v[168:169], v[168:169], v[234:235]
	v_pk_add_f32 v[170:171], v[170:171], v[236:237]
	v_pk_add_f32 v[172:173], v[172:173], v[230:231]
	v_pk_add_f32 v[174:175], v[174:175], v[232:233]
	v_pk_add_f32 v[176:177], v[176:177], v[234:235]
	v_pk_add_f32 v[178:179], v[178:179], v[236:237]
; __global__ void __launch_bounds__(512, 2) hybrid_fwd(Args args) {
;     ...
;                 for (int j = 0; j < 16; ++j) {
;                     if (j < w && tl - j >= 0) {
;                         const u32x4 v = *(const u32x4*)(xp - (size_t)j * 512);
;                         if (j == 0) x0 = v;
; #pragma unroll
;                         for (int e = 0; e < 4; ++e) { sum[2 * e] += __builtin_bit_cast(float, v[e] << 16); sum[2 * e + 1] += __builtin_bit_cast(float, v[e] & 0xffff0000u); }
;                     }
;                 }
.Lp3d_s24:
	s_or_b64 exec, exec, s[58:59]
	s_and_saveexec_b64 s[58:59], s[22:23]
	s_cbranch_execz .Lp3d_s25
	v_pk_add_f32 v[180:181], v[180:181], v[230:231]
	v_pk_add_f32 v[182:183], v[182:183], v[232:233]
	v_pk_add_f32 v[184:185], v[184:185], v[234:235]
	v_pk_add_f32 v[186:187], v[186:187], v[236:237]
	v_pk_add_f32 v[188:189], v[188:189], v[230:231]
	v_pk_add_f32 v[190:191], v[190:191], v[232:233]
	v_pk_add_f32 v[192:193], v[192:193], v[234:235]
	v_pk_add_f32 v[194:195], v[194:195], v[236:237]
	v_pk_add_f32 v[196:197], v[196:197], v[230:231]
	v_pk_add_f32 v[198:199], v[198:199], v[232:233]
	v_pk_add_f32 v[200:201], v[200:201], v[234:235]
	v_pk_add_f32 v[202:203], v[202:203], v[236:237]
	v_pk_add_f32 v[204:205], v[204:205], v[230:231]
	v_pk_add_f32 v[206:207], v[206:207], v[232:233]
	v_pk_add_f32 v[208:209], v[208:209], v[234:235]
	v_pk_add_f32 v[210:211], v[210:211], v[236:237]
	v_pk_add_f32 v[212:213], v[212:213], v[230:231]
	v_pk_add_f32 v[214:215], v[214:215], v[232:233]
	v_pk_add_f32 v[216:217], v[216:217], v[234:235]
	v_pk_add_f32 v[218:219], v[218:219], v[236:237]
	v_pk_add_f32 v[222:223], v[222:223], v[230:231]
	v_pk_add_f32 v[224:225], v[224:225], v[232:233]
	v_pk_add_f32 v[226:227], v[226:227], v[234:235]
	v_pk_add_f32 v[228:229], v[228:229], v[236:237]
.Lp3d_s25:
	s_or_b64 exec, exec, s[58:59]
	v_lshlrev_b32_e32 v230, 16, v72
	v_and_b32_e32 v231, 0xffff0000, v72
	v_lshlrev_b32_e32 v232, 16, v73
	v_and_b32_e32 v233, 0xffff0000, v73
	v_lshlrev_b32_e32 v234, 16, v74
	v_and_b32_e32 v235, 0xffff0000, v74
	v_lshlrev_b32_e32 v236, 16, v75
	v_and_b32_e32 v237, 0xffff0000, v75
	s_and_saveexec_b64 s[58:59], s[14:15]
	s_cbranch_execz .Lp3d_s26
	v_pk_add_f32 v[164:165], v[164:165], v[230:231]
	v_pk_add_f32 v[166:167], v[166:167], v[232:233]
	v_pk_add_f32 v[168:169], v[168:169], v[234:235]
	v_pk_add_f32 v[170:171], v[170:171], v[236:237]
.Lp3d_s26:
	s_or_b64 exec, exec, s[58:59]
	s_and_saveexec_b64 s[58:59], s[22:23]
	s_cbranch_execz .Lp3d_s27
	v_pk_add_f32 v[172:173], v[172:173], v[230:231]
	v_pk_add_f32 v[174:175], v[174:175], v[232:233]
	v_pk_add_f32 v[176:177], v[176:177], v[234:235]
	v_pk_add_f32 v[178:179], v[178:179], v[236:237]
	v_pk_add_f32 v[180:181], v[180:181], v[230:231]
	v_pk_add_f32 v[182:183], v[182:183], v[232:233]
	v_pk_add_f32 v[184:185], v[184:185], v[234:235]
	v_pk_add_f32 v[186:187], v[186:187], v[236:237]
	v_pk_add_f32 v[188:189], v[188:189], v[230:231]
	v_pk_add_f32 v[190:191], v[190:191], v[232:233]
	v_pk_add_f32 v[192:193], v[192:193], v[234:235]
	v_pk_add_f32 v[194:195], v[194:195], v[236:237]
	v_pk_add_f32 v[196:197], v[196:197], v[230:231]
	v_pk_add_f32 v[198:199], v[198:199], v[232:233]
	v_pk_add_f32 v[200:201], v[200:201], v[234:235]
	v_pk_add_f32 v[202:203], v[202:203], v[236:237]
	v_pk_add_f32 v[204:205], v[204:205], v[230:231]
	v_pk_add_f32 v[206:207], v[206:207], v[232:233]
	v_pk_add_f32 v[208:209], v[208:209], v[234:235]
	v_pk_add_f32 v[210:211], v[210:211], v[236:237]
	v_pk_add_f32 v[212:213], v[212:213], v[230:231]
	v_pk_add_f32 v[214:215], v[214:215], v[232:233]
	v_pk_add_f32 v[216:217], v[216:217], v[234:235]
	v_pk_add_f32 v[218:219], v[218:219], v[236:237]
	v_pk_add_f32 v[222:223], v[222:223], v[230:231]
	v_pk_add_f32 v[224:225], v[224:225], v[232:233]
	v_pk_add_f32 v[226:227], v[226:227], v[234:235]
	v_pk_add_f32 v[228:229], v[228:229], v[236:237]
.Lp3d_s27:
	s_or_b64 exec, exec, s[58:59]
	v_lshlrev_b32_e32 v230, 16, v68
	v_and_b32_e32 v231, 0xffff0000, v68
	v_lshlrev_b32_e32 v232, 16, v69
	v_and_b32_e32 v233, 0xffff0000, v69
	v_lshlrev_b32_e32 v234, 16, v70
	v_and_b32_e32 v235, 0xffff0000, v70
	v_lshlrev_b32_e32 v236, 16, v71
	v_and_b32_e32 v237, 0xffff0000, v71
	s_and_saveexec_b64 s[58:59], s[22:23]
	s_cbranch_execz .Lp3d_s28
	v_pk_add_f32 v[164:165], v[164:165], v[230:231]
	v_pk_add_f32 v[166:167], v[166:167], v[232:233]
	v_pk_add_f32 v[168:169], v[168:169], v[234:235]
	v_pk_add_f32 v[170:171], v[170:171], v[236:237]
	v_pk_add_f32 v[172:173], v[172:173], v[230:231]
	v_pk_add_f32 v[174:175], v[174:175], v[232:233]
	v_pk_add_f32 v[176:177], v[176:177], v[234:235]
	v_pk_add_f32 v[178:179], v[178:179], v[236:237]
	v_pk_add_f32 v[180:181], v[180:181], v[230:231]
	v_pk_add_f32 v[182:183], v[182:183], v[232:233]
	v_pk_add_f32 v[184:185], v[184:185], v[234:235]
	v_pk_add_f32 v[186:187], v[186:187], v[236:237]
	v_pk_add_f32 v[188:189], v[188:189], v[230:231]
	v_pk_add_f32 v[190:191], v[190:191], v[232:233]
	v_pk_add_f32 v[192:193], v[192:193], v[234:235]
	v_pk_add_f32 v[194:195], v[194:195], v[236:237]
	v_pk_add_f32 v[196:197], v[196:197], v[230:231]
	v_pk_add_f32 v[198:199], v[198:199], v[232:233]
	v_pk_add_f32 v[200:201], v[200:201], v[234:235]
	v_pk_add_f32 v[202:203], v[202:203], v[236:237]
	v_pk_add_f32 v[204:205], v[204:205], v[230:231]
	v_pk_add_f32 v[206:207], v[206:207], v[232:233]
	v_pk_add_f32 v[208:209], v[208:209], v[234:235]
	v_pk_add_f32 v[210:211], v[210:211], v[236:237]
	v_pk_add_f32 v[212:213], v[212:213], v[230:231]
	v_pk_add_f32 v[214:215], v[214:215], v[232:233]
	v_pk_add_f32 v[216:217], v[216:217], v[234:235]
	v_pk_add_f32 v[218:219], v[218:219], v[236:237]
	v_pk_add_f32 v[222:223], v[222:223], v[230:231]
	v_pk_add_f32 v[224:225], v[224:225], v[232:233]
	v_pk_add_f32 v[226:227], v[226:227], v[234:235]
	v_pk_add_f32 v[228:229], v[228:229], v[236:237]
; __global__ void __launch_bounds__(512, 2) hybrid_fwd(Args args) {
;     ...
;                 for (int j = 0; j < 16; ++j) {
;                     if (j < w && tl - j >= 0) {
;                         const u32x4 v = *(const u32x4*)(xp - (size_t)j * 512);
;                         if (j == 0) x0 = v;
; #pragma unroll
;                         for (int e = 0; e < 4; ++e) { sum[2 * e] += __builtin_bit_cast(float, v[e] << 16); sum[2 * e + 1] += __builtin_bit_cast(float, v[e] & 0xffff0000u); }
;                     }
;                 }
.Lp3d_s28:
	s_or_b64 exec, exec, s[58:59]
	v_lshlrev_b32_e32 v230, 16, v64
	v_and_b32_e32 v231, 0xffff0000, v64
	v_lshlrev_b32_e32 v232, 16, v65
	v_and_b32_e32 v233, 0xffff0000, v65
	v_lshlrev_b32_e32 v234, 16, v66
	v_and_b32_e32 v235, 0xffff0000, v66
	v_lshlrev_b32_e32 v236, 16, v67
	v_and_b32_e32 v237, 0xffff0000, v67
	s_and_saveexec_b64 s[58:59], s[22:23]
	s_cbranch_execz .Lp3d_s29
	v_pk_add_f32 v[164:165], v[164:165], v[230:231]
	v_pk_add_f32 v[166:167], v[166:167], v[232:233]
	v_pk_add_f32 v[168:169], v[168:169], v[234:235]
	v_pk_add_f32 v[170:171], v[170:171], v[236:237]
	v_pk_add_f32 v[172:173], v[172:173], v[230:231]
	v_pk_add_f32 v[174:175], v[174:175], v[232:233]
	v_pk_add_f32 v[176:177], v[176:177], v[234:235]
	v_pk_add_f32 v[178:179], v[178:179], v[236:237]
	v_pk_add_f32 v[180:181], v[180:181], v[230:231]
	v_pk_add_f32 v[182:183], v[182:183], v[232:233]
	v_pk_add_f32 v[184:185], v[184:185], v[234:235]
	v_pk_add_f32 v[186:187], v[186:187], v[236:237]
	v_pk_add_f32 v[188:189], v[188:189], v[230:231]
	v_pk_add_f32 v[190:191], v[190:191], v[232:233]
	v_pk_add_f32 v[192:193], v[192:193], v[234:235]
	v_pk_add_f32 v[194:195], v[194:195], v[236:237]
	v_pk_add_f32 v[196:197], v[196:197], v[230:231]
	v_pk_add_f32 v[198:199], v[198:199], v[232:233]
	v_pk_add_f32 v[200:201], v[200:201], v[234:235]
	v_pk_add_f32 v[202:203], v[202:203], v[236:237]
	v_pk_add_f32 v[204:205], v[204:205], v[230:231]
	v_pk_add_f32 v[206:207], v[206:207], v[232:233]
	v_pk_add_f32 v[208:209], v[208:209], v[234:235]
	v_pk_add_f32 v[210:211], v[210:211], v[236:237]
	v_pk_add_f32 v[212:213], v[212:213], v[230:231]
	v_pk_add_f32 v[214:215], v[214:215], v[232:233]
	v_pk_add_f32 v[216:217], v[216:217], v[234:235]
	v_pk_add_f32 v[218:219], v[218:219], v[236:237]
.Lp3d_s29:
	s_or_b64 exec, exec, s[58:59]
	v_lshlrev_b32_e32 v230, 16, v60
	v_and_b32_e32 v231, 0xffff0000, v60
	v_lshlrev_b32_e32 v232, 16, v61
	v_and_b32_e32 v233, 0xffff0000, v61
	v_lshlrev_b32_e32 v234, 16, v62
	v_and_b32_e32 v235, 0xffff0000, v62
	v_lshlrev_b32_e32 v236, 16, v63
	v_and_b32_e32 v237, 0xffff0000, v63
	s_and_saveexec_b64 s[58:59], s[22:23]
	s_cbranch_execz .Lp3d_s30
	v_pk_add_f32 v[164:165], v[164:165], v[230:231]
	v_pk_add_f32 v[166:167], v[166:167], v[232:233]
	v_pk_add_f32 v[168:169], v[168:169], v[234:235]
	v_pk_add_f32 v[170:171], v[170:171], v[236:237]
	v_pk_add_f32 v[172:173], v[172:173], v[230:231]
	v_pk_add_f32 v[174:175], v[174:175], v[232:233]
	v_pk_add_f32 v[176:177], v[176:177], v[234:235]
	v_pk_add_f32 v[178:179], v[178:179], v[236:237]
	v_pk_add_f32 v[180:181], v[180:181], v[230:231]
	v_pk_add_f32 v[182:183], v[182:183], v[232:233]
	v_pk_add_f32 v[184:185], v[184:185], v[234:235]
	v_pk_add_f32 v[186:187], v[186:187], v[236:237]
	v_pk_add_f32 v[188:189], v[188:189], v[230:231]
	v_pk_add_f32 v[190:191], v[190:191], v[232:233]
	v_pk_add_f32 v[192:193], v[192:193], v[234:235]
	v_pk_add_f32 v[194:195], v[194:195], v[236:237]
	v_pk_add_f32 v[196:197], v[196:197], v[230:231]
	v_pk_add_f32 v[198:199], v[198:199], v[232:233]
	v_pk_add_f32 v[200:201], v[200:201], v[234:235]
	v_pk_add_f32 v[202:203], v[202:203], v[236:237]
	v_pk_add_f32 v[204:205], v[204:205], v[230:231]
	v_pk_add_f32 v[206:207], v[206:207], v[232:233]
	v_pk_add_f32 v[208:209], v[208:209], v[234:235]
	v_pk_add_f32 v[210:211], v[210:211], v[236:237]
.Lp3d_s30:
	s_or_b64 exec, exec, s[58:59]
	v_lshlrev_b32_e32 v230, 16, v56
	v_and_b32_e32 v231, 0xffff0000, v56
	v_lshlrev_b32_e32 v232, 16, v57
	v_and_b32_e32 v233, 0xffff0000, v57
	v_lshlrev_b32_e32 v234, 16, v58
	v_and_b32_e32 v235, 0xffff0000, v58
	v_lshlrev_b32_e32 v236, 16, v59
	v_and_b32_e32 v237, 0xffff0000, v59
	s_and_saveexec_b64 s[58:59], s[22:23]
	s_cbranch_execz .Lp3d_s31
	v_pk_add_f32 v[164:165], v[164:165], v[230:231]
	v_pk_add_f32 v[166:167], v[166:167], v[232:233]
	v_pk_add_f32 v[168:169], v[168:169], v[234:235]
	v_pk_add_f32 v[170:171], v[170:171], v[236:237]
	v_pk_add_f32 v[172:173], v[172:173], v[230:231]
	v_pk_add_f32 v[174:175], v[174:175], v[232:233]
	v_pk_add_f32 v[176:177], v[176:177], v[234:235]
	v_pk_add_f32 v[178:179], v[178:179], v[236:237]
	v_pk_add_f32 v[180:181], v[180:181], v[230:231]
	v_pk_add_f32 v[182:183], v[182:183], v[232:233]
	v_pk_add_f32 v[184:185], v[184:185], v[234:235]
	v_pk_add_f32 v[186:187], v[186:187], v[236:237]
	v_pk_add_f32 v[188:189], v[188:189], v[230:231]
	v_pk_add_f32 v[190:191], v[190:191], v[232:233]
	v_pk_add_f32 v[192:193], v[192:193], v[234:235]
	v_pk_add_f32 v[194:195], v[194:195], v[236:237]
	v_pk_add_f32 v[196:197], v[196:197], v[230:231]
	v_pk_add_f32 v[198:199], v[198:199], v[232:233]
	v_pk_add_f32 v[200:201], v[200:201], v[234:235]
	v_pk_add_f32 v[202:203], v[202:203], v[236:237]
.Lp3d_s31:
	s_or_b64 exec, exec, s[58:59]
	v_lshlrev_b32_e32 v230, 16, v52
	v_and_b32_e32 v231, 0xffff0000, v52
	v_lshlrev_b32_e32 v232, 16, v53
	v_and_b32_e32 v233, 0xffff0000, v53
	v_lshlrev_b32_e32 v234, 16, v54
	v_and_b32_e32 v235, 0xffff0000, v54
	v_lshlrev_b32_e32 v236, 16, v55
	v_and_b32_e32 v237, 0xffff0000, v55
	s_and_saveexec_b64 s[58:59], s[22:23]
	s_cbranch_execz .Lp3d_s32
	v_pk_add_f32 v[164:165], v[164:165], v[230:231]
	v_pk_add_f32 v[166:167], v[166:167], v[232:233]
	v_pk_add_f32 v[168:169], v[168:169], v[234:235]
	v_pk_add_f32 v[170:171], v[170:171], v[236:237]
	v_pk_add_f32 v[172:173], v[172:173], v[230:231]
	v_pk_add_f32 v[174:175], v[174:175], v[232:233]
	v_pk_add_f32 v[176:177], v[176:177], v[234:235]
	v_pk_add_f32 v[178:179], v[178:179], v[236:237]
	v_pk_add_f32 v[180:181], v[180:181], v[230:231]
	v_pk_add_f32 v[182:183], v[182:183], v[232:233]
	v_pk_add_f32 v[184:185], v[184:185], v[234:235]
	v_pk_add_f32 v[186:187], v[186:187], v[236:237]
	v_pk_add_f32 v[188:189], v[188:189], v[230:231]
	v_pk_add_f32 v[190:191], v[190:191], v[232:233]
	v_pk_add_f32 v[192:193], v[192:193], v[234:235]
	v_pk_add_f32 v[194:195], v[194:195], v[236:237]
; __device__ __forceinline__ unsigned cvt_pk_bf16(float lo, float hi) { f32x2_t v = {lo, hi}; bf16x2_t b = __builtin_convertvector(v, bf16x2_t); return __builtin_bit_cast(unsigned, b); }
; __global__ void __launch_bounds__(512, 2) hybrid_fwd(Args args) {
;     ...
;                 for (int j = 0; j < 16; ++j) {
;                     if (j < w && tl - j >= 0) {
;                         const u32x4 v = *(const u32x4*)(xp - (size_t)j * 512);
;                         if (j == 0) x0 = v;
; #pragma unroll
;                         for (int e = 0; e < 4; ++e) { sum[2 * e] += __builtin_bit_cast(float, v[e] << 16); sum[2 * e + 1] += __builtin_bit_cast(float, v[e] & 0xffff0000u); }
;                     }
;                 }
;                 const float inv = 1.0f / (float)(tl + 1 < w ? tl + 1 : w);
;                 float p[8];
; #pragma unroll
;                 for (int e = 0; e < 4; ++e) { p[2 * e] = sum[2 * e] * inv - __builtin_bit_cast(float, x0[e] << 16); p[2 * e + 1] = sum[2 * e + 1] * inv - __builtin_bit_cast(float, x0[e] & 0xffff0000u); }
;                 u32x4 o; o.x = cvt_pk_bf16(p[0], p[1]); o.y = cvt_pk_bf16(p[2], p[3]); o.z = cvt_pk_bf16(p[4], p[5]); o.w = cvt_pk_bf16(p[6], p[7]);
;                 *(u32x4*)(POOLED + (size_t)t * 512 + cg8 * 8) = o;
.Lp3d_s32:
	s_or_b64 exec, exec, s[58:59]
	v_lshlrev_b32_e32 v230, 16, v48
	v_and_b32_e32 v231, 0xffff0000, v48
	v_lshlrev_b32_e32 v232, 16, v49
	v_and_b32_e32 v233, 0xffff0000, v49
	v_lshlrev_b32_e32 v234, 16, v50
	v_and_b32_e32 v235, 0xffff0000, v50
	v_lshlrev_b32_e32 v236, 16, v51
	v_and_b32_e32 v237, 0xffff0000, v51
	s_and_saveexec_b64 s[58:59], s[22:23]
	s_cbranch_execz .Lp3d_s33
	v_pk_add_f32 v[164:165], v[164:165], v[230:231]
	v_pk_add_f32 v[166:167], v[166:167], v[232:233]
	v_pk_add_f32 v[168:169], v[168:169], v[234:235]
	v_pk_add_f32 v[170:171], v[170:171], v[236:237]
	v_pk_add_f32 v[172:173], v[172:173], v[230:231]
	v_pk_add_f32 v[174:175], v[174:175], v[232:233]
	v_pk_add_f32 v[176:177], v[176:177], v[234:235]
	v_pk_add_f32 v[178:179], v[178:179], v[236:237]
	v_pk_add_f32 v[180:181], v[180:181], v[230:231]
	v_pk_add_f32 v[182:183], v[182:183], v[232:233]
	v_pk_add_f32 v[184:185], v[184:185], v[234:235]
	v_pk_add_f32 v[186:187], v[186:187], v[236:237]
.Lp3d_s33:
	s_or_b64 exec, exec, s[58:59]
	v_lshlrev_b32_e32 v230, 16, v44
	v_and_b32_e32 v231, 0xffff0000, v44
	v_lshlrev_b32_e32 v232, 16, v45
	v_and_b32_e32 v233, 0xffff0000, v45
	v_lshlrev_b32_e32 v234, 16, v46
	v_and_b32_e32 v235, 0xffff0000, v46
	v_lshlrev_b32_e32 v236, 16, v47
	v_and_b32_e32 v237, 0xffff0000, v47
	s_and_saveexec_b64 s[58:59], s[22:23]
	s_cbranch_execz .Lp3d_s34
	v_pk_add_f32 v[164:165], v[164:165], v[230:231]
	v_pk_add_f32 v[166:167], v[166:167], v[232:233]
	v_pk_add_f32 v[168:169], v[168:169], v[234:235]
	v_pk_add_f32 v[170:171], v[170:171], v[236:237]
	v_pk_add_f32 v[172:173], v[172:173], v[230:231]
	v_pk_add_f32 v[174:175], v[174:175], v[232:233]
	v_pk_add_f32 v[176:177], v[176:177], v[234:235]
	v_pk_add_f32 v[178:179], v[178:179], v[236:237]
.Lp3d_s34:
	s_or_b64 exec, exec, s[58:59]
	v_lshlrev_b32_e32 v230, 16, v40
	v_and_b32_e32 v231, 0xffff0000, v40
	v_lshlrev_b32_e32 v232, 16, v41
	v_and_b32_e32 v233, 0xffff0000, v41
	v_lshlrev_b32_e32 v234, 16, v42
	v_and_b32_e32 v235, 0xffff0000, v42
	v_lshlrev_b32_e32 v236, 16, v43
	v_and_b32_e32 v237, 0xffff0000, v43
	s_and_saveexec_b64 s[58:59], s[22:23]
	s_cbranch_execz .Lp3d_s35
	v_pk_add_f32 v[164:165], v[164:165], v[230:231]
	v_pk_add_f32 v[166:167], v[166:167], v[232:233]
	v_pk_add_f32 v[168:169], v[168:169], v[234:235]
	v_pk_add_f32 v[170:171], v[170:171], v[236:237]
.Lp3d_s35:
	s_or_b64 exec, exec, s[58:59]
	v_add_u32_e32 v12, 1, v31
	v_min_i32_e32 v12, v12, v28
	v_cvt_f32_i32_e32 v13, v12
	v_div_scale_f32 v24, s[58:59], v13, v13, 1.0
	v_rcp_f32_e32 v25, v24
	v_div_scale_f32 v14, vcc, 1.0, v13, 1.0
	v_fma_f32 v15, -v24, v25, 1.0
	v_fmac_f32_e32 v25, v15, v25
	v_mul_f32_e32 v15, v14, v25
	v_fma_f32 v16, -v24, v15, v14
	v_fmac_f32_e32 v15, v16, v25
	v_fma_f32 v24, -v24, v15, v14
	v_div_fmas_f32 v24, v24, v25, v15
	v_div_fixup_f32 v24, v24, v13, 1.0
	v_lshlrev_b32_e32 v230, 16, v100
	v_and_b32_e32 v231, 0xffff0000, v100
	v_lshlrev_b32_e32 v232, 16, v101
	v_and_b32_e32 v233, 0xffff0000, v101
	v_lshlrev_b32_e32 v234, 16, v102
	v_and_b32_e32 v235, 0xffff0000, v102
	v_lshlrev_b32_e32 v236, 16, v103
	v_and_b32_e32 v237, 0xffff0000, v103
	v_pk_fma_f32 v[164:165], v[24:25], v[164:165], v[230:231] op_sel_hi:[0,1,1] neg_lo:[0,0,1] neg_hi:[0,0,1]
	v_pk_fma_f32 v[166:167], v[24:25], v[166:167], v[232:233] op_sel_hi:[0,1,1] neg_lo:[0,0,1] neg_hi:[0,0,1]
	v_pk_fma_f32 v[168:169], v[24:25], v[168:169], v[234:235] op_sel_hi:[0,1,1] neg_lo:[0,0,1] neg_hi:[0,0,1]
	v_pk_fma_f32 v[170:171], v[24:25], v[170:171], v[236:237] op_sel_hi:[0,1,1] neg_lo:[0,0,1] neg_hi:[0,0,1]
	v_cvt_pk_bf16_f32 v0, v164, v165
	v_cvt_pk_bf16_f32 v1, v166, v167
	v_cvt_pk_bf16_f32 v2, v168, v169
	v_cvt_pk_bf16_f32 v3, v170, v171
	global_store_dwordx4 v[238:239], v[0:3], off
	v_add_u32_e32 v12, 2, v31
	v_min_i32_e32 v12, v12, v28
	v_cvt_f32_i32_e32 v13, v12
	v_div_scale_f32 v24, s[58:59], v13, v13, 1.0
	v_rcp_f32_e32 v25, v24
	v_div_scale_f32 v14, vcc, 1.0, v13, 1.0
	v_fma_f32 v15, -v24, v25, 1.0
	v_fmac_f32_e32 v25, v15, v25
	v_mul_f32_e32 v15, v14, v25
	v_fma_f32 v16, -v24, v15, v14
	v_fmac_f32_e32 v15, v16, v25
	v_fma_f32 v24, -v24, v15, v14
	v_div_fmas_f32 v24, v24, v25, v15
	v_div_fixup_f32 v24, v24, v13, 1.0
	v_lshlrev_b32_e32 v230, 16, v104
	v_and_b32_e32 v231, 0xffff0000, v104
	v_lshlrev_b32_e32 v232, 16, v105
	v_and_b32_e32 v233, 0xffff0000, v105
	v_lshlrev_b32_e32 v234, 16, v106
	v_and_b32_e32 v235, 0xffff0000, v106
	v_lshlrev_b32_e32 v236, 16, v107
	v_and_b32_e32 v237, 0xffff0000, v107
	v_pk_fma_f32 v[172:173], v[24:25], v[172:173], v[230:231] op_sel_hi:[0,1,1] neg_lo:[0,0,1] neg_hi:[0,0,1]
	v_pk_fma_f32 v[174:175], v[24:25], v[174:175], v[232:233] op_sel_hi:[0,1,1] neg_lo:[0,0,1] neg_hi:[0,0,1]
	v_pk_fma_f32 v[176:177], v[24:25], v[176:177], v[234:235] op_sel_hi:[0,1,1] neg_lo:[0,0,1] neg_hi:[0,0,1]
	v_pk_fma_f32 v[178:179], v[24:25], v[178:179], v[236:237] op_sel_hi:[0,1,1] neg_lo:[0,0,1] neg_hi:[0,0,1]
	v_cvt_pk_bf16_f32 v0, v172, v173
	v_cvt_pk_bf16_f32 v1, v174, v175
	v_cvt_pk_bf16_f32 v2, v176, v177
	v_cvt_pk_bf16_f32 v3, v178, v179
	global_store_dwordx4 v[238:239], v[0:3], off offset:1024
	v_add_u32_e32 v12, 3, v31
	v_min_i32_e32 v12, v12, v28
	v_cvt_f32_i32_e32 v13, v12
	v_div_scale_f32 v24, s[58:59], v13, v13, 1.0
	v_rcp_f32_e32 v25, v24
	v_div_scale_f32 v14, vcc, 1.0, v13, 1.0
	v_fma_f32 v15, -v24, v25, 1.0
	v_fmac_f32_e32 v25, v15, v25
	v_mul_f32_e32 v15, v14, v25
	v_fma_f32 v16, -v24, v15, v14
	v_fmac_f32_e32 v15, v16, v25
	v_fma_f32 v24, -v24, v15, v14
	v_div_fmas_f32 v24, v24, v25, v15
	v_div_fixup_f32 v24, v24, v13, 1.0
	v_lshlrev_b32_e32 v230, 16, v108
	v_and_b32_e32 v231, 0xffff0000, v108
	v_lshlrev_b32_e32 v232, 16, v109
; __device__ __forceinline__ unsigned cvt_pk_bf16(float lo, float hi) { f32x2_t v = {lo, hi}; bf16x2_t b = __builtin_convertvector(v, bf16x2_t); return __builtin_bit_cast(unsigned, b); }
; __global__ void __launch_bounds__(512, 2) hybrid_fwd(Args args) {
;     ...
;                 const float inv = 1.0f / (float)(tl + 1 < w ? tl + 1 : w);
;                 float p[8];
; #pragma unroll
;                 for (int e = 0; e < 4; ++e) { p[2 * e] = sum[2 * e] * inv - __builtin_bit_cast(float, x0[e] << 16); p[2 * e + 1] = sum[2 * e + 1] * inv - __builtin_bit_cast(float, x0[e] & 0xffff0000u); }
;                 u32x4 o; o.x = cvt_pk_bf16(p[0], p[1]); o.y = cvt_pk_bf16(p[2], p[3]); o.z = cvt_pk_bf16(p[4], p[5]); o.w = cvt_pk_bf16(p[6], p[7]);
;                 *(u32x4*)(POOLED + (size_t)t * 512 + cg8 * 8) = o;
	v_and_b32_e32 v233, 0xffff0000, v109
	v_lshlrev_b32_e32 v234, 16, v110
	v_and_b32_e32 v235, 0xffff0000, v110
	v_lshlrev_b32_e32 v236, 16, v111
	v_and_b32_e32 v237, 0xffff0000, v111
	v_pk_fma_f32 v[180:181], v[24:25], v[180:181], v[230:231] op_sel_hi:[0,1,1] neg_lo:[0,0,1] neg_hi:[0,0,1]
	v_pk_fma_f32 v[182:183], v[24:25], v[182:183], v[232:233] op_sel_hi:[0,1,1] neg_lo:[0,0,1] neg_hi:[0,0,1]
	v_pk_fma_f32 v[184:185], v[24:25], v[184:185], v[234:235] op_sel_hi:[0,1,1] neg_lo:[0,0,1] neg_hi:[0,0,1]
	v_pk_fma_f32 v[186:187], v[24:25], v[186:187], v[236:237] op_sel_hi:[0,1,1] neg_lo:[0,0,1] neg_hi:[0,0,1]
	v_cvt_pk_bf16_f32 v0, v180, v181
	v_cvt_pk_bf16_f32 v1, v182, v183
	v_cvt_pk_bf16_f32 v2, v184, v185
	v_cvt_pk_bf16_f32 v3, v186, v187
	global_store_dwordx4 v[238:239], v[0:3], off offset:2048
	v_add_u32_e32 v12, 4, v31
	v_min_i32_e32 v12, v12, v28
	v_cvt_f32_i32_e32 v13, v12
	v_div_scale_f32 v24, s[58:59], v13, v13, 1.0
	v_rcp_f32_e32 v25, v24
	v_div_scale_f32 v14, vcc, 1.0, v13, 1.0
	v_fma_f32 v15, -v24, v25, 1.0
	v_fmac_f32_e32 v25, v15, v25
	v_mul_f32_e32 v15, v14, v25
	v_fma_f32 v16, -v24, v15, v14
	v_fmac_f32_e32 v15, v16, v25
	v_fma_f32 v24, -v24, v15, v14
	v_div_fmas_f32 v24, v24, v25, v15
	v_div_fixup_f32 v24, v24, v13, 1.0
	v_lshlrev_b32_e32 v230, 16, v112
	v_and_b32_e32 v231, 0xffff0000, v112
	v_lshlrev_b32_e32 v232, 16, v113
	v_and_b32_e32 v233, 0xffff0000, v113
	v_lshlrev_b32_e32 v234, 16, v114
	v_and_b32_e32 v235, 0xffff0000, v114
	v_lshlrev_b32_e32 v236, 16, v115
	v_and_b32_e32 v237, 0xffff0000, v115
	v_pk_fma_f32 v[188:189], v[24:25], v[188:189], v[230:231] op_sel_hi:[0,1,1] neg_lo:[0,0,1] neg_hi:[0,0,1]
	v_pk_fma_f32 v[190:191], v[24:25], v[190:191], v[232:233] op_sel_hi:[0,1,1] neg_lo:[0,0,1] neg_hi:[0,0,1]
	v_pk_fma_f32 v[192:193], v[24:25], v[192:193], v[234:235] op_sel_hi:[0,1,1] neg_lo:[0,0,1] neg_hi:[0,0,1]
	v_pk_fma_f32 v[194:195], v[24:25], v[194:195], v[236:237] op_sel_hi:[0,1,1] neg_lo:[0,0,1] neg_hi:[0,0,1]
	v_cvt_pk_bf16_f32 v0, v188, v189
	v_cvt_pk_bf16_f32 v1, v190, v191
	v_cvt_pk_bf16_f32 v2, v192, v193
	v_cvt_pk_bf16_f32 v3, v194, v195
	global_store_dwordx4 v[238:239], v[0:3], off offset:3072
	v_add_u32_e32 v12, 5, v31
	v_min_i32_e32 v12, v12, v28
	v_cvt_f32_i32_e32 v13, v12
	v_div_scale_f32 v24, s[58:59], v13, v13, 1.0
	v_rcp_f32_e32 v25, v24
	v_div_scale_f32 v14, vcc, 1.0, v13, 1.0
	v_fma_f32 v15, -v24, v25, 1.0
	v_fmac_f32_e32 v25, v15, v25
	v_mul_f32_e32 v15, v14, v25
	v_fma_f32 v16, -v24, v15, v14
	v_fmac_f32_e32 v15, v16, v25
	v_fma_f32 v24, -v24, v15, v14
	v_div_fmas_f32 v24, v24, v25, v15
	v_div_fixup_f32 v24, v24, v13, 1.0
	v_lshlrev_b32_e32 v230, 16, v116
	v_and_b32_e32 v231, 0xffff0000, v116
	v_lshlrev_b32_e32 v232, 16, v117
	v_and_b32_e32 v233, 0xffff0000, v117
	v_lshlrev_b32_e32 v234, 16, v118
	v_and_b32_e32 v235, 0xffff0000, v118
	v_lshlrev_b32_e32 v236, 16, v119
	v_and_b32_e32 v237, 0xffff0000, v119
	v_pk_fma_f32 v[196:197], v[24:25], v[196:197], v[230:231] op_sel_hi:[0,1,1] neg_lo:[0,0,1] neg_hi:[0,0,1]
	v_pk_fma_f32 v[198:199], v[24:25], v[198:199], v[232:233] op_sel_hi:[0,1,1] neg_lo:[0,0,1] neg_hi:[0,0,1]
	v_pk_fma_f32 v[200:201], v[24:25], v[200:201], v[234:235] op_sel_hi:[0,1,1] neg_lo:[0,0,1] neg_hi:[0,0,1]
	v_pk_fma_f32 v[202:203], v[24:25], v[202:203], v[236:237] op_sel_hi:[0,1,1] neg_lo:[0,0,1] neg_hi:[0,0,1]
	v_cvt_pk_bf16_f32 v0, v196, v197
	v_cvt_pk_bf16_f32 v1, v198, v199
	v_cvt_pk_bf16_f32 v2, v200, v201
	v_cvt_pk_bf16_f32 v3, v202, v203
	v_add_co_u32_e32 v240, vcc, 0x1000, v238
	s_nop 1
	v_addc_co_u32_e32 v241, vcc, 0, v239, vcc
	global_store_dwordx4 v[240:241], v[0:3], off
	v_add_u32_e32 v12, 6, v31
	v_min_i32_e32 v12, v12, v28
	v_cvt_f32_i32_e32 v13, v12
	v_div_scale_f32 v24, s[58:59], v13, v13, 1.0
	v_rcp_f32_e32 v25, v24
	v_div_scale_f32 v14, vcc, 1.0, v13, 1.0
	v_fma_f32 v15, -v24, v25, 1.0
	v_fmac_f32_e32 v25, v15, v25
	v_mul_f32_e32 v15, v14, v25
	v_fma_f32 v16, -v24, v15, v14
	v_fmac_f32_e32 v15, v16, v25
	v_fma_f32 v24, -v24, v15, v14
	v_div_fmas_f32 v24, v24, v25, v15
	v_div_fixup_f32 v24, v24, v13, 1.0
	v_lshlrev_b32_e32 v230, 16, v120
	v_and_b32_e32 v231, 0xffff0000, v120
	v_lshlrev_b32_e32 v232, 16, v121
	v_and_b32_e32 v233, 0xffff0000, v121
	v_lshlrev_b32_e32 v234, 16, v122
	v_and_b32_e32 v235, 0xffff0000, v122
	v_lshlrev_b32_e32 v236, 16, v123
	v_and_b32_e32 v237, 0xffff0000, v123
	v_pk_fma_f32 v[204:205], v[24:25], v[204:205], v[230:231] op_sel_hi:[0,1,1] neg_lo:[0,0,1] neg_hi:[0,0,1]
	v_pk_fma_f32 v[206:207], v[24:25], v[206:207], v[232:233] op_sel_hi:[0,1,1] neg_lo:[0,0,1] neg_hi:[0,0,1]
	v_pk_fma_f32 v[208:209], v[24:25], v[208:209], v[234:235] op_sel_hi:[0,1,1] neg_lo:[0,0,1] neg_hi:[0,0,1]
	v_pk_fma_f32 v[210:211], v[24:25], v[210:211], v[236:237] op_sel_hi:[0,1,1] neg_lo:[0,0,1] neg_hi:[0,0,1]
	v_cvt_pk_bf16_f32 v0, v204, v205
	v_cvt_pk_bf16_f32 v1, v206, v207
	v_cvt_pk_bf16_f32 v2, v208, v209
	v_cvt_pk_bf16_f32 v3, v210, v211
	global_store_dwordx4 v[240:241], v[0:3], off offset:1024
	v_add_u32_e32 v12, 7, v31
	v_min_i32_e32 v12, v12, v28
	v_cvt_f32_i32_e32 v13, v12
	v_div_scale_f32 v24, s[58:59], v13, v13, 1.0
	v_rcp_f32_e32 v25, v24
	v_div_scale_f32 v14, vcc, 1.0, v13, 1.0
	v_fma_f32 v15, -v24, v25, 1.0
	v_fmac_f32_e32 v25, v15, v25
	v_mul_f32_e32 v15, v14, v25
	v_fma_f32 v16, -v24, v15, v14
	v_fmac_f32_e32 v15, v16, v25
	v_fma_f32 v24, -v24, v15, v14
	v_div_fmas_f32 v24, v24, v25, v15
	v_div_fixup_f32 v24, v24, v13, 1.0
	v_lshlrev_b32_e32 v230, 16, v124
	v_and_b32_e32 v231, 0xffff0000, v124
	v_lshlrev_b32_e32 v232, 16, v125
	v_and_b32_e32 v233, 0xffff0000, v125
	v_lshlrev_b32_e32 v234, 16, v126
	v_and_b32_e32 v235, 0xffff0000, v126
; __device__ __forceinline__ unsigned cvt_pk_bf16(float lo, float hi) { f32x2_t v = {lo, hi}; bf16x2_t b = __builtin_convertvector(v, bf16x2_t); return __builtin_bit_cast(unsigned, b); }
; __global__ void __launch_bounds__(512, 2) hybrid_fwd(Args args) {
;     ...
;                 float sum[8];
; #pragma unroll
;                 for (int e = 0; e < 8; ++e) sum[e] = 0.f;
;                 u32x4 x0 = (u32x4){0u, 0u, 0u, 0u};
; #pragma unroll
;                 for (int j = 0; j < 16; ++j) {
;                     if (j < w && tl - j >= 0) {
;                         const u32x4 v = *(const u32x4*)(xp - (size_t)j * 512);
;                         if (j == 0) x0 = v;
; #pragma unroll
;                         for (int e = 0; e < 4; ++e) { sum[2 * e] += __builtin_bit_cast(float, v[e] << 16); sum[2 * e + 1] += __builtin_bit_cast(float, v[e] & 0xffff0000u); }
;                     }
;                 }
;                 const float inv = 1.0f / (float)(tl + 1 < w ? tl + 1 : w);
;                 float p[8];
; #pragma unroll
;                 for (int e = 0; e < 4; ++e) { p[2 * e] = sum[2 * e] * inv - __builtin_bit_cast(float, x0[e] << 16); p[2 * e + 1] = sum[2 * e + 1] * inv - __builtin_bit_cast(float, x0[e] & 0xffff0000u); }
;                 u32x4 o; o.x = cvt_pk_bf16(p[0], p[1]); o.y = cvt_pk_bf16(p[2], p[3]); o.z = cvt_pk_bf16(p[4], p[5]); o.w = cvt_pk_bf16(p[6], p[7]);
;                 *(u32x4*)(POOLED + (size_t)t * 512 + cg8 * 8) = o;
	v_lshlrev_b32_e32 v236, 16, v127
	v_and_b32_e32 v237, 0xffff0000, v127
	v_pk_fma_f32 v[212:213], v[24:25], v[212:213], v[230:231] op_sel_hi:[0,1,1] neg_lo:[0,0,1] neg_hi:[0,0,1]
	v_pk_fma_f32 v[214:215], v[24:25], v[214:215], v[232:233] op_sel_hi:[0,1,1] neg_lo:[0,0,1] neg_hi:[0,0,1]
	v_pk_fma_f32 v[216:217], v[24:25], v[216:217], v[234:235] op_sel_hi:[0,1,1] neg_lo:[0,0,1] neg_hi:[0,0,1]
	v_pk_fma_f32 v[218:219], v[24:25], v[218:219], v[236:237] op_sel_hi:[0,1,1] neg_lo:[0,0,1] neg_hi:[0,0,1]
	v_cvt_pk_bf16_f32 v0, v212, v213
	v_cvt_pk_bf16_f32 v1, v214, v215
	v_cvt_pk_bf16_f32 v2, v216, v217
	v_cvt_pk_bf16_f32 v3, v218, v219
	global_store_dwordx4 v[240:241], v[0:3], off offset:2048
	v_add_u32_e32 v12, 8, v31
	v_min_i32_e32 v12, v12, v28
	v_cvt_f32_i32_e32 v13, v12
	v_div_scale_f32 v24, s[58:59], v13, v13, 1.0
	v_rcp_f32_e32 v25, v24
	v_div_scale_f32 v14, vcc, 1.0, v13, 1.0
	v_fma_f32 v15, -v24, v25, 1.0
	v_fmac_f32_e32 v25, v15, v25
	v_mul_f32_e32 v15, v14, v25
	v_fma_f32 v16, -v24, v15, v14
	v_fmac_f32_e32 v15, v16, v25
	v_fma_f32 v24, -v24, v15, v14
	v_div_fmas_f32 v24, v24, v25, v15
	v_div_fixup_f32 v24, v24, v13, 1.0
	v_lshlrev_b32_e32 v230, 16, v128
	v_and_b32_e32 v231, 0xffff0000, v128
	v_lshlrev_b32_e32 v232, 16, v129
	v_and_b32_e32 v233, 0xffff0000, v129
	v_lshlrev_b32_e32 v234, 16, v130
	v_and_b32_e32 v235, 0xffff0000, v130
	v_lshlrev_b32_e32 v236, 16, v131
	v_and_b32_e32 v237, 0xffff0000, v131
	v_pk_fma_f32 v[222:223], v[24:25], v[222:223], v[230:231] op_sel_hi:[0,1,1] neg_lo:[0,0,1] neg_hi:[0,0,1]
	v_pk_fma_f32 v[224:225], v[24:25], v[224:225], v[232:233] op_sel_hi:[0,1,1] neg_lo:[0,0,1] neg_hi:[0,0,1]
	v_pk_fma_f32 v[226:227], v[24:25], v[226:227], v[234:235] op_sel_hi:[0,1,1] neg_lo:[0,0,1] neg_hi:[0,0,1]
	v_pk_fma_f32 v[228:229], v[24:25], v[228:229], v[236:237] op_sel_hi:[0,1,1] neg_lo:[0,0,1] neg_hi:[0,0,1]
	v_cvt_pk_bf16_f32 v0, v222, v223
	v_cvt_pk_bf16_f32 v1, v224, v225
	v_cvt_pk_bf16_f32 v2, v226, v227
	v_cvt_pk_bf16_f32 v3, v228, v229
	global_store_dwordx4 v[240:241], v[0:3], off offset:3072
	v_mov_b32_e32 v164, 0
	v_mov_b32_e32 v165, 0
	v_mov_b32_e32 v166, 0
	v_mov_b32_e32 v167, 0
	v_mov_b32_e32 v168, 0
	v_mov_b32_e32 v169, 0
	v_mov_b32_e32 v170, 0
	v_mov_b32_e32 v171, 0
	v_mov_b32_e32 v172, 0
	v_mov_b32_e32 v173, 0
	v_mov_b32_e32 v174, 0
	v_mov_b32_e32 v175, 0
	v_mov_b32_e32 v176, 0
	v_mov_b32_e32 v177, 0
	v_mov_b32_e32 v178, 0
	v_mov_b32_e32 v179, 0
	v_mov_b32_e32 v180, 0
	v_mov_b32_e32 v181, 0
	v_mov_b32_e32 v182, 0
	v_mov_b32_e32 v183, 0
	v_mov_b32_e32 v184, 0
	v_mov_b32_e32 v185, 0
	v_mov_b32_e32 v186, 0
	v_mov_b32_e32 v187, 0
	v_mov_b32_e32 v188, 0
	v_mov_b32_e32 v189, 0
	v_mov_b32_e32 v190, 0
	v_mov_b32_e32 v191, 0
	v_mov_b32_e32 v192, 0
	v_mov_b32_e32 v193, 0
	v_mov_b32_e32 v194, 0
	v_mov_b32_e32 v195, 0
	v_mov_b32_e32 v196, 0
	v_mov_b32_e32 v197, 0
	v_mov_b32_e32 v198, 0
	v_mov_b32_e32 v199, 0
	v_mov_b32_e32 v200, 0
	v_mov_b32_e32 v201, 0
	v_mov_b32_e32 v202, 0
	v_mov_b32_e32 v203, 0
	v_mov_b32_e32 v204, 0
	v_mov_b32_e32 v205, 0
	v_mov_b32_e32 v206, 0
	v_mov_b32_e32 v207, 0
	v_mov_b32_e32 v208, 0
	v_mov_b32_e32 v209, 0
	v_mov_b32_e32 v210, 0
	v_mov_b32_e32 v211, 0
	v_mov_b32_e32 v212, 0
	v_mov_b32_e32 v213, 0
	v_mov_b32_e32 v214, 0
	v_mov_b32_e32 v215, 0
	v_mov_b32_e32 v216, 0
	v_mov_b32_e32 v217, 0
	v_mov_b32_e32 v218, 0
	v_mov_b32_e32 v219, 0
	v_mov_b32_e32 v222, 0
	v_mov_b32_e32 v223, 0
	v_mov_b32_e32 v224, 0
	v_mov_b32_e32 v225, 0
	v_mov_b32_e32 v226, 0
	v_mov_b32_e32 v227, 0
	v_mov_b32_e32 v228, 0
	v_mov_b32_e32 v229, 0
	v_lshlrev_b32_e32 v230, 16, v160
	v_and_b32_e32 v231, 0xffff0000, v160
	v_lshlrev_b32_e32 v232, 16, v161
	v_and_b32_e32 v233, 0xffff0000, v161
	v_lshlrev_b32_e32 v234, 16, v162
	v_and_b32_e32 v235, 0xffff0000, v162
	v_lshlrev_b32_e32 v236, 16, v163
	v_and_b32_e32 v237, 0xffff0000, v163
	v_pk_add_f32 v[222:223], v[222:223], v[230:231]
	v_pk_add_f32 v[224:225], v[224:225], v[232:233]
	v_pk_add_f32 v[226:227], v[226:227], v[234:235]
	v_pk_add_f32 v[228:229], v[228:229], v[236:237]
	v_lshlrev_b32_e32 v230, 16, v156
	v_and_b32_e32 v231, 0xffff0000, v156
	v_lshlrev_b32_e32 v232, 16, v157
	v_and_b32_e32 v233, 0xffff0000, v157
	v_lshlrev_b32_e32 v234, 16, v158
	v_and_b32_e32 v235, 0xffff0000, v158
	v_lshlrev_b32_e32 v236, 16, v159
	v_and_b32_e32 v237, 0xffff0000, v159
	v_pk_add_f32 v[212:213], v[212:213], v[230:231]
	v_pk_add_f32 v[214:215], v[214:215], v[232:233]
	v_pk_add_f32 v[216:217], v[216:217], v[234:235]
	v_pk_add_f32 v[218:219], v[218:219], v[236:237]
	v_pk_add_f32 v[222:223], v[222:223], v[230:231]
	v_pk_add_f32 v[224:225], v[224:225], v[232:233]
	v_pk_add_f32 v[226:227], v[226:227], v[234:235]
	v_pk_add_f32 v[228:229], v[228:229], v[236:237]
	v_lshlrev_b32_e32 v230, 16, v152
	v_and_b32_e32 v231, 0xffff0000, v152
	v_lshlrev_b32_e32 v232, 16, v153
	v_and_b32_e32 v233, 0xffff0000, v153
	v_lshlrev_b32_e32 v234, 16, v154
	v_and_b32_e32 v235, 0xffff0000, v154
	v_lshlrev_b32_e32 v236, 16, v155
	v_and_b32_e32 v237, 0xffff0000, v155
	v_pk_add_f32 v[204:205], v[204:205], v[230:231]
	v_pk_add_f32 v[206:207], v[206:207], v[232:233]
	v_pk_add_f32 v[208:209], v[208:209], v[234:235]
	v_pk_add_f32 v[210:211], v[210:211], v[236:237]
	v_pk_add_f32 v[212:213], v[212:213], v[230:231]
	v_pk_add_f32 v[214:215], v[214:215], v[232:233]
	v_pk_add_f32 v[216:217], v[216:217], v[234:235]
	v_pk_add_f32 v[218:219], v[218:219], v[236:237]
	s_and_saveexec_b64 s[58:59], s[10:11]
	s_cbranch_execz .Lp3d_s36
	v_pk_add_f32 v[222:223], v[222:223], v[230:231]
	v_pk_add_f32 v[224:225], v[224:225], v[232:233]
	v_pk_add_f32 v[226:227], v[226:227], v[234:235]
	v_pk_add_f32 v[228:229], v[228:229], v[236:237]
; __global__ void __launch_bounds__(512, 2) hybrid_fwd(Args args) {
;     ...
;                 for (int j = 0; j < 16; ++j) {
;                     if (j < w && tl - j >= 0) {
;                         const u32x4 v = *(const u32x4*)(xp - (size_t)j * 512);
;                         if (j == 0) x0 = v;
; #pragma unroll
;                         for (int e = 0; e < 4; ++e) { sum[2 * e] += __builtin_bit_cast(float, v[e] << 16); sum[2 * e + 1] += __builtin_bit_cast(float, v[e] & 0xffff0000u); }
;                     }
;                 }
.Lp3d_s36:
	s_or_b64 exec, exec, s[58:59]
	v_lshlrev_b32_e32 v230, 16, v148
	v_and_b32_e32 v231, 0xffff0000, v148
	v_lshlrev_b32_e32 v232, 16, v149
	v_and_b32_e32 v233, 0xffff0000, v149
	v_lshlrev_b32_e32 v234, 16, v150
	v_and_b32_e32 v235, 0xffff0000, v150
	v_lshlrev_b32_e32 v236, 16, v151
	v_and_b32_e32 v237, 0xffff0000, v151
	v_pk_add_f32 v[196:197], v[196:197], v[230:231]
	v_pk_add_f32 v[198:199], v[198:199], v[232:233]
	v_pk_add_f32 v[200:201], v[200:201], v[234:235]
	v_pk_add_f32 v[202:203], v[202:203], v[236:237]
	v_pk_add_f32 v[204:205], v[204:205], v[230:231]
	v_pk_add_f32 v[206:207], v[206:207], v[232:233]
	v_pk_add_f32 v[208:209], v[208:209], v[234:235]
	v_pk_add_f32 v[210:211], v[210:211], v[236:237]
	s_and_saveexec_b64 s[58:59], s[10:11]
	s_cbranch_execz .Lp3d_s37
	v_pk_add_f32 v[212:213], v[212:213], v[230:231]
	v_pk_add_f32 v[214:215], v[214:215], v[232:233]
	v_pk_add_f32 v[216:217], v[216:217], v[234:235]
	v_pk_add_f32 v[218:219], v[218:219], v[236:237]
	v_pk_add_f32 v[222:223], v[222:223], v[230:231]
	v_pk_add_f32 v[224:225], v[224:225], v[232:233]
	v_pk_add_f32 v[226:227], v[226:227], v[234:235]
	v_pk_add_f32 v[228:229], v[228:229], v[236:237]
.Lp3d_s37:
	s_or_b64 exec, exec, s[58:59]
	v_lshlrev_b32_e32 v230, 16, v144
	v_and_b32_e32 v231, 0xffff0000, v144
	v_lshlrev_b32_e32 v232, 16, v145
	v_and_b32_e32 v233, 0xffff0000, v145
	v_lshlrev_b32_e32 v234, 16, v146
	v_and_b32_e32 v235, 0xffff0000, v146
	v_lshlrev_b32_e32 v236, 16, v147
	v_and_b32_e32 v237, 0xffff0000, v147
	v_pk_add_f32 v[188:189], v[188:189], v[230:231]
	v_pk_add_f32 v[190:191], v[190:191], v[232:233]
	v_pk_add_f32 v[192:193], v[192:193], v[234:235]
	v_pk_add_f32 v[194:195], v[194:195], v[236:237]
	v_pk_add_f32 v[196:197], v[196:197], v[230:231]
	v_pk_add_f32 v[198:199], v[198:199], v[232:233]
	v_pk_add_f32 v[200:201], v[200:201], v[234:235]
	v_pk_add_f32 v[202:203], v[202:203], v[236:237]
	s_and_saveexec_b64 s[58:59], s[10:11]
	s_cbranch_execz .Lp3d_s38
	v_pk_add_f32 v[204:205], v[204:205], v[230:231]
	v_pk_add_f32 v[206:207], v[206:207], v[232:233]
	v_pk_add_f32 v[208:209], v[208:209], v[234:235]
	v_pk_add_f32 v[210:211], v[210:211], v[236:237]
	v_pk_add_f32 v[212:213], v[212:213], v[230:231]
	v_pk_add_f32 v[214:215], v[214:215], v[232:233]
	v_pk_add_f32 v[216:217], v[216:217], v[234:235]
	v_pk_add_f32 v[218:219], v[218:219], v[236:237]

; __global__ void __launch_bounds__(512, 2) hybrid_fwd(Args args) {
;     ...
;                 for (int j = 0; j < 16; ++j) {
;                     if (j < w && tl - j >= 0) {
;                         const u32x4 v = *(const u32x4*)(xp - (size_t)j * 512);
;                         if (j == 0) x0 = v;
; #pragma unroll
;                         for (int e = 0; e < 4; ++e) { sum[2 * e] += __builtin_bit_cast(float, v[e] << 16); sum[2 * e + 1] += __builtin_bit_cast(float, v[e] & 0xffff0000u); }
;                     }
;                 }
.Lp3d_s39:
	s_or_b64 exec, exec, s[58:59]
	v_lshlrev_b32_e32 v230, 16, v140
	v_and_b32_e32 v231, 0xffff0000, v140
	v_lshlrev_b32_e32 v232, 16, v141
	v_and_b32_e32 v233, 0xffff0000, v141
	v_lshlrev_b32_e32 v234, 16, v142
	v_and_b32_e32 v235, 0xffff0000, v142
	v_lshlrev_b32_e32 v236, 16, v143
	v_and_b32_e32 v237, 0xffff0000, v143
	v_pk_add_f32 v[180:181], v[180:181], v[230:231]
	v_pk_add_f32 v[182:183], v[182:183], v[232:233]
	v_pk_add_f32 v[184:185], v[184:185], v[234:235]
	v_pk_add_f32 v[186:187], v[186:187], v[236:237]
	v_pk_add_f32 v[188:189], v[188:189], v[230:231]
	v_pk_add_f32 v[190:191], v[190:191], v[232:233]
	v_pk_add_f32 v[192:193], v[192:193], v[234:235]
	v_pk_add_f32 v[194:195], v[194:195], v[236:237]
	s_and_saveexec_b64 s[58:59], s[10:11]
	s_cbranch_execz .Lp3d_s40
	v_pk_add_f32 v[196:197], v[196:197], v[230:231]
	v_pk_add_f32 v[198:199], v[198:199], v[232:233]
	v_pk_add_f32 v[200:201], v[200:201], v[234:235]
	v_pk_add_f32 v[202:203], v[202:203], v[236:237]
	v_pk_add_f32 v[204:205], v[204:205], v[230:231]
	v_pk_add_f32 v[206:207], v[206:207], v[232:233]
	v_pk_add_f32 v[208:209], v[208:209], v[234:235]
	v_pk_add_f32 v[210:211], v[210:211], v[236:237]

; __global__ void __launch_bounds__(512, 2) hybrid_fwd(Args args) {
;     ...
;                 for (int j = 0; j < 16; ++j) {
;                     if (j < w && tl - j >= 0) {
;                         const u32x4 v = *(const u32x4*)(xp - (size_t)j * 512);
;                         if (j == 0) x0 = v;
; #pragma unroll
;                         for (int e = 0; e < 4; ++e) { sum[2 * e] += __builtin_bit_cast(float, v[e] << 16); sum[2 * e + 1] += __builtin_bit_cast(float, v[e] & 0xffff0000u); }
;                     }
;                 }
.Lp3d_s41:
	s_or_b64 exec, exec, s[58:59]
	v_lshlrev_b32_e32 v230, 16, v136
	v_and_b32_e32 v231, 0xffff0000, v136
	v_lshlrev_b32_e32 v232, 16, v137
	v_and_b32_e32 v233, 0xffff0000, v137
	v_lshlrev_b32_e32 v234, 16, v138
	v_and_b32_e32 v235, 0xffff0000, v138
	v_lshlrev_b32_e32 v236, 16, v139
	v_and_b32_e32 v237, 0xffff0000, v139
	v_pk_add_f32 v[172:173], v[172:173], v[230:231]
	v_pk_add_f32 v[174:175], v[174:175], v[232:233]
	v_pk_add_f32 v[176:177], v[176:177], v[234:235]
	v_pk_add_f32 v[178:179], v[178:179], v[236:237]
	v_pk_add_f32 v[180:181], v[180:181], v[230:231]
	v_pk_add_f32 v[182:183], v[182:183], v[232:233]
	v_pk_add_f32 v[184:185], v[184:185], v[234:235]
	v_pk_add_f32 v[186:187], v[186:187], v[236:237]
	s_and_saveexec_b64 s[58:59], s[10:11]
	s_cbranch_execz .Lp3d_s42
	v_pk_add_f32 v[188:189], v[188:189], v[230:231]
	v_pk_add_f32 v[190:191], v[190:191], v[232:233]
	v_pk_add_f32 v[192:193], v[192:193], v[234:235]
	v_pk_add_f32 v[194:195], v[194:195], v[236:237]
	v_pk_add_f32 v[196:197], v[196:197], v[230:231]
	v_pk_add_f32 v[198:199], v[198:199], v[232:233]
	v_pk_add_f32 v[200:201], v[200:201], v[234:235]
	v_pk_add_f32 v[202:203], v[202:203], v[236:237]

; __global__ void __launch_bounds__(512, 2) hybrid_fwd(Args args) {
;     ...
;                 for (int j = 0; j < 16; ++j) {
;                     if (j < w && tl - j >= 0) {
;                         const u32x4 v = *(const u32x4*)(xp - (size_t)j * 512);
;                         if (j == 0) x0 = v;
; #pragma unroll
;                         for (int e = 0; e < 4; ++e) { sum[2 * e] += __builtin_bit_cast(float, v[e] << 16); sum[2 * e + 1] += __builtin_bit_cast(float, v[e] & 0xffff0000u); }
;                     }
;                 }
.Lp3d_s43:
	s_or_b64 exec, exec, s[58:59]
	v_lshlrev_b32_e32 v230, 16, v132
	v_and_b32_e32 v231, 0xffff0000, v132
	v_lshlrev_b32_e32 v232, 16, v133
	v_and_b32_e32 v233, 0xffff0000, v133
	v_lshlrev_b32_e32 v234, 16, v134
	v_and_b32_e32 v235, 0xffff0000, v134
	v_lshlrev_b32_e32 v236, 16, v135
	v_and_b32_e32 v237, 0xffff0000, v135
	v_pk_add_f32 v[164:165], v[164:165], v[230:231]
	v_pk_add_f32 v[166:167], v[166:167], v[232:233]
	v_pk_add_f32 v[168:169], v[168:169], v[234:235]
	v_pk_add_f32 v[170:171], v[170:171], v[236:237]
	v_pk_add_f32 v[172:173], v[172:173], v[230:231]
	v_pk_add_f32 v[174:175], v[174:175], v[232:233]
	v_pk_add_f32 v[176:177], v[176:177], v[234:235]
	v_pk_add_f32 v[178:179], v[178:179], v[236:237]
	s_and_saveexec_b64 s[58:59], s[10:11]
	s_cbranch_execz .Lp3d_s44
	v_pk_add_f32 v[180:181], v[180:181], v[230:231]
	v_pk_add_f32 v[182:183], v[182:183], v[232:233]
	v_pk_add_f32 v[184:185], v[184:185], v[234:235]
	v_pk_add_f32 v[186:187], v[186:187], v[236:237]
	v_pk_add_f32 v[188:189], v[188:189], v[230:231]
	v_pk_add_f32 v[190:191], v[190:191], v[232:233]
	v_pk_add_f32 v[192:193], v[192:193], v[234:235]
	v_pk_add_f32 v[194:195], v[194:195], v[236:237]

; __global__ void __launch_bounds__(512, 2) hybrid_fwd(Args args) {
;     ...
;                 for (int j = 0; j < 16; ++j) {
;                     if (j < w && tl - j >= 0) {
;                         const u32x4 v = *(const u32x4*)(xp - (size_t)j * 512);
;                         if (j == 0) x0 = v;
; #pragma unroll
;                         for (int e = 0; e < 4; ++e) { sum[2 * e] += __builtin_bit_cast(float, v[e] << 16); sum[2 * e + 1] += __builtin_bit_cast(float, v[e] & 0xffff0000u); }
;                     }
;                 }
.Lp3d_s45:
	s_or_b64 exec, exec, s[58:59]
	v_lshlrev_b32_e32 v230, 16, v128
	v_and_b32_e32 v231, 0xffff0000, v128
	v_lshlrev_b32_e32 v232, 16, v129
	v_and_b32_e32 v233, 0xffff0000, v129
	v_lshlrev_b32_e32 v234, 16, v130
	v_and_b32_e32 v235, 0xffff0000, v130
	v_lshlrev_b32_e32 v236, 16, v131
	v_and_b32_e32 v237, 0xffff0000, v131
	v_pk_add_f32 v[164:165], v[164:165], v[230:231]
	v_pk_add_f32 v[166:167], v[166:167], v[232:233]
	v_pk_add_f32 v[168:169], v[168:169], v[234:235]
	v_pk_add_f32 v[170:171], v[170:171], v[236:237]
	s_and_saveexec_b64 s[58:59], s[10:11]
	s_cbranch_execz .Lp3d_s46
	v_pk_add_f32 v[172:173], v[172:173], v[230:231]
	v_pk_add_f32 v[174:175], v[174:175], v[232:233]
	v_pk_add_f32 v[176:177], v[176:177], v[234:235]
	v_pk_add_f32 v[178:179], v[178:179], v[236:237]
	v_pk_add_f32 v[180:181], v[180:181], v[230:231]
	v_pk_add_f32 v[182:183], v[182:183], v[232:233]
	v_pk_add_f32 v[184:185], v[184:185], v[234:235]
	v_pk_add_f32 v[186:187], v[186:187], v[236:237]

; __global__ void __launch_bounds__(512, 2) hybrid_fwd(Args args) {
;     ...
;                 for (int j = 0; j < 16; ++j) {
;                     if (j < w && tl - j >= 0) {
;                         const u32x4 v = *(const u32x4*)(xp - (size_t)j * 512);
;                         if (j == 0) x0 = v;
; #pragma unroll
;                         for (int e = 0; e < 4; ++e) { sum[2 * e] += __builtin_bit_cast(float, v[e] << 16); sum[2 * e + 1] += __builtin_bit_cast(float, v[e] & 0xffff0000u); }
;                     }
;                 }
.Lp3d_s48:
	s_or_b64 exec, exec, s[58:59]
	v_lshlrev_b32_e32 v230, 16, v124
	v_and_b32_e32 v231, 0xffff0000, v124
	v_lshlrev_b32_e32 v232, 16, v125
	v_and_b32_e32 v233, 0xffff0000, v125
	v_lshlrev_b32_e32 v234, 16, v126
	v_and_b32_e32 v235, 0xffff0000, v126
	v_lshlrev_b32_e32 v236, 16, v127
	v_and_b32_e32 v237, 0xffff0000, v127
	s_and_saveexec_b64 s[58:59], s[10:11]
	s_cbranch_execz .Lp3d_s49
	v_pk_add_f32 v[164:165], v[164:165], v[230:231]
	v_pk_add_f32 v[166:167], v[166:167], v[232:233]
	v_pk_add_f32 v[168:169], v[168:169], v[234:235]
	v_pk_add_f32 v[170:171], v[170:171], v[236:237]
	v_pk_add_f32 v[172:173], v[172:173], v[230:231]
	v_pk_add_f32 v[174:175], v[174:175], v[232:233]
	v_pk_add_f32 v[176:177], v[176:177], v[234:235]
	v_pk_add_f32 v[178:179], v[178:179], v[236:237]

; __global__ void __launch_bounds__(512, 2) hybrid_fwd(Args args) {
;     ...
;                 for (int j = 0; j < 16; ++j) {
;                     if (j < w && tl - j >= 0) {
;                         const u32x4 v = *(const u32x4*)(xp - (size_t)j * 512);
;                         if (j == 0) x0 = v;
; #pragma unroll
;                         for (int e = 0; e < 4; ++e) { sum[2 * e] += __builtin_bit_cast(float, v[e] << 16); sum[2 * e + 1] += __builtin_bit_cast(float, v[e] & 0xffff0000u); }
;                     }
;                 }
.Lp3d_s51:
	s_or_b64 exec, exec, s[58:59]
	v_lshlrev_b32_e32 v230, 16, v120
	v_and_b32_e32 v231, 0xffff0000, v120
	v_lshlrev_b32_e32 v232, 16, v121
	v_and_b32_e32 v233, 0xffff0000, v121
	v_lshlrev_b32_e32 v234, 16, v122
	v_and_b32_e32 v235, 0xffff0000, v122
	v_lshlrev_b32_e32 v236, 16, v123
	v_and_b32_e32 v237, 0xffff0000, v123
	s_and_saveexec_b64 s[58:59], s[10:11]
	s_cbranch_execz .Lp3d_s52
	v_pk_add_f32 v[164:165], v[164:165], v[230:231]
	v_pk_add_f32 v[166:167], v[166:167], v[232:233]
	v_pk_add_f32 v[168:169], v[168:169], v[234:235]
	v_pk_add_f32 v[170:171], v[170:171], v[236:237]

; __global__ void __launch_bounds__(512, 2) hybrid_fwd(Args args) {
;     ...
;                 for (int j = 0; j < 16; ++j) {
;                     if (j < w && tl - j >= 0) {
;                         const u32x4 v = *(const u32x4*)(xp - (size_t)j * 512);
;                         if (j == 0) x0 = v;
; #pragma unroll
;                         for (int e = 0; e < 4; ++e) { sum[2 * e] += __builtin_bit_cast(float, v[e] << 16); sum[2 * e + 1] += __builtin_bit_cast(float, v[e] & 0xffff0000u); }
;                     }
;                 }
.Lp3d_s54:
	s_or_b64 exec, exec, s[58:59]
	v_lshlrev_b32_e32 v230, 16, v116
	v_and_b32_e32 v231, 0xffff0000, v116
	v_lshlrev_b32_e32 v232, 16, v117
	v_and_b32_e32 v233, 0xffff0000, v117
	v_lshlrev_b32_e32 v234, 16, v118
	v_and_b32_e32 v235, 0xffff0000, v118
	v_lshlrev_b32_e32 v236, 16, v119
	v_and_b32_e32 v237, 0xffff0000, v119
	s_and_saveexec_b64 s[58:59], s[14:15]
	s_cbranch_execz .Lp3d_s55
	v_pk_add_f32 v[164:165], v[164:165], v[230:231]
	v_pk_add_f32 v[166:167], v[166:167], v[232:233]
	v_pk_add_f32 v[168:169], v[168:169], v[234:235]
	v_pk_add_f32 v[170:171], v[170:171], v[236:237]
	v_pk_add_f32 v[172:173], v[172:173], v[230:231]
	v_pk_add_f32 v[174:175], v[174:175], v[232:233]
	v_pk_add_f32 v[176:177], v[176:177], v[234:235]
	v_pk_add_f32 v[178:179], v[178:179], v[236:237]
	v_pk_add_f32 v[180:181], v[180:181], v[230:231]
	v_pk_add_f32 v[182:183], v[182:183], v[232:233]
	v_pk_add_f32 v[184:185], v[184:185], v[234:235]
	v_pk_add_f32 v[186:187], v[186:187], v[236:237]
	v_pk_add_f32 v[188:189], v[188:189], v[230:231]
	v_pk_add_f32 v[190:191], v[190:191], v[232:233]
	v_pk_add_f32 v[192:193], v[192:193], v[234:235]
	v_pk_add_f32 v[194:195], v[194:195], v[236:237]

; __global__ void __launch_bounds__(512, 2) hybrid_fwd(Args args) {
;     ...
;                 for (int j = 0; j < 16; ++j) {
;                     if (j < w && tl - j >= 0) {
;                         const u32x4 v = *(const u32x4*)(xp - (size_t)j * 512);
;                         if (j == 0) x0 = v;
; #pragma unroll
;                         for (int e = 0; e < 4; ++e) { sum[2 * e] += __builtin_bit_cast(float, v[e] << 16); sum[2 * e + 1] += __builtin_bit_cast(float, v[e] & 0xffff0000u); }
;                     }
;                 }
.Lp3d_s56:
	s_or_b64 exec, exec, s[58:59]
	v_lshlrev_b32_e32 v230, 16, v112
	v_and_b32_e32 v231, 0xffff0000, v112
	v_lshlrev_b32_e32 v232, 16, v113
	v_and_b32_e32 v233, 0xffff0000, v113
	v_lshlrev_b32_e32 v234, 16, v114
	v_and_b32_e32 v235, 0xffff0000, v114
	v_lshlrev_b32_e32 v236, 16, v115
	v_and_b32_e32 v237, 0xffff0000, v115
	s_and_saveexec_b64 s[58:59], s[14:15]
	s_cbranch_execz .Lp3d_s57
	v_pk_add_f32 v[164:165], v[164:165], v[230:231]
	v_pk_add_f32 v[166:167], v[166:167], v[232:233]
	v_pk_add_f32 v[168:169], v[168:169], v[234:235]
	v_pk_add_f32 v[170:171], v[170:171], v[236:237]
	v_pk_add_f32 v[172:173], v[172:173], v[230:231]
	v_pk_add_f32 v[174:175], v[174:175], v[232:233]
	v_pk_add_f32 v[176:177], v[176:177], v[234:235]
	v_pk_add_f32 v[178:179], v[178:179], v[236:237]
	v_pk_add_f32 v[180:181], v[180:181], v[230:231]
	v_pk_add_f32 v[182:183], v[182:183], v[232:233]
	v_pk_add_f32 v[184:185], v[184:185], v[234:235]
	v_pk_add_f32 v[186:187], v[186:187], v[236:237]

; __global__ void __launch_bounds__(512, 2) hybrid_fwd(Args args) {
;     ...
;                 for (int j = 0; j < 16; ++j) {
;                     if (j < w && tl - j >= 0) {
;                         const u32x4 v = *(const u32x4*)(xp - (size_t)j * 512);
;                         if (j == 0) x0 = v;
; #pragma unroll
;                         for (int e = 0; e < 4; ++e) { sum[2 * e] += __builtin_bit_cast(float, v[e] << 16); sum[2 * e + 1] += __builtin_bit_cast(float, v[e] & 0xffff0000u); }
;                     }
;                 }
.Lp3d_s58:
	s_or_b64 exec, exec, s[58:59]
	v_lshlrev_b32_e32 v230, 16, v108
	v_and_b32_e32 v231, 0xffff0000, v108
	v_lshlrev_b32_e32 v232, 16, v109
	v_and_b32_e32 v233, 0xffff0000, v109
	v_lshlrev_b32_e32 v234, 16, v110
	v_and_b32_e32 v235, 0xffff0000, v110
	v_lshlrev_b32_e32 v236, 16, v111
	v_and_b32_e32 v237, 0xffff0000, v111
	s_and_saveexec_b64 s[58:59], s[14:15]
	s_cbranch_execz .Lp3d_s59
	v_pk_add_f32 v[164:165], v[164:165], v[230:231]
	v_pk_add_f32 v[166:167], v[166:167], v[232:233]
	v_pk_add_f32 v[168:169], v[168:169], v[234:235]
	v_pk_add_f32 v[170:171], v[170:171], v[236:237]
	v_pk_add_f32 v[172:173], v[172:173], v[230:231]
	v_pk_add_f32 v[174:175], v[174:175], v[232:233]
	v_pk_add_f32 v[176:177], v[176:177], v[234:235]
	v_pk_add_f32 v[178:179], v[178:179], v[236:237]

; __global__ void __launch_bounds__(512, 2) hybrid_fwd(Args args) {
;     ...
;                 for (int j = 0; j < 16; ++j) {
;                     if (j < w && tl - j >= 0) {
;                         const u32x4 v = *(const u32x4*)(xp - (size_t)j * 512);
;                         if (j == 0) x0 = v;
; #pragma unroll
;                         for (int e = 0; e < 4; ++e) { sum[2 * e] += __builtin_bit_cast(float, v[e] << 16); sum[2 * e + 1] += __builtin_bit_cast(float, v[e] & 0xffff0000u); }
;                     }
;                 }
.Lp3d_s60:
	s_or_b64 exec, exec, s[58:59]
	v_lshlrev_b32_e32 v230, 16, v104
	v_and_b32_e32 v231, 0xffff0000, v104
	v_lshlrev_b32_e32 v232, 16, v105
	v_and_b32_e32 v233, 0xffff0000, v105
	v_lshlrev_b32_e32 v234, 16, v106
	v_and_b32_e32 v235, 0xffff0000, v106
	v_lshlrev_b32_e32 v236, 16, v107
	v_and_b32_e32 v237, 0xffff0000, v107
	s_and_saveexec_b64 s[58:59], s[14:15]
	s_cbranch_execz .Lp3d_s61
	v_pk_add_f32 v[164:165], v[164:165], v[230:231]
	v_pk_add_f32 v[166:167], v[166:167], v[232:233]
	v_pk_add_f32 v[168:169], v[168:169], v[234:235]
	v_pk_add_f32 v[170:171], v[170:171], v[236:237]

; __global__ void __launch_bounds__(512, 2) hybrid_fwd(Args args) {
;     ...
;                 for (int j = 0; j < 16; ++j) {
;                     if (j < w && tl - j >= 0) {
;                         const u32x4 v = *(const u32x4*)(xp - (size_t)j * 512);
;                         if (j == 0) x0 = v;
; #pragma unroll
;                         for (int e = 0; e < 4; ++e) { sum[2 * e] += __builtin_bit_cast(float, v[e] << 16); sum[2 * e + 1] += __builtin_bit_cast(float, v[e] & 0xffff0000u); }
;                     }
;                 }
.Lp3d_s62:
	s_or_b64 exec, exec, s[58:59]
	v_lshlrev_b32_e32 v230, 16, v100
	v_and_b32_e32 v231, 0xffff0000, v100
	v_lshlrev_b32_e32 v232, 16, v101
	v_and_b32_e32 v233, 0xffff0000, v101
	v_lshlrev_b32_e32 v234, 16, v102
	v_and_b32_e32 v235, 0xffff0000, v102
	v_lshlrev_b32_e32 v236, 16, v103
	v_and_b32_e32 v237, 0xffff0000, v103
	s_and_saveexec_b64 s[58:59], s[22:23]
	s_cbranch_execz .Lp3d_s63
	v_pk_add_f32 v[164:165], v[164:165], v[230:231]
	v_pk_add_f32 v[166:167], v[166:167], v[232:233]
	v_pk_add_f32 v[168:169], v[168:169], v[234:235]
	v_pk_add_f32 v[170:171], v[170:171], v[236:237]
	v_pk_add_f32 v[172:173], v[172:173], v[230:231]
	v_pk_add_f32 v[174:175], v[174:175], v[232:233]
	v_pk_add_f32 v[176:177], v[176:177], v[234:235]
	v_pk_add_f32 v[178:179], v[178:179], v[236:237]
	v_pk_add_f32 v[180:181], v[180:181], v[230:231]
	v_pk_add_f32 v[182:183], v[182:183], v[232:233]
	v_pk_add_f32 v[184:185], v[184:185], v[234:235]
	v_pk_add_f32 v[186:187], v[186:187], v[236:237]
	v_pk_add_f32 v[188:189], v[188:189], v[230:231]
	v_pk_add_f32 v[190:191], v[190:191], v[232:233]
	v_pk_add_f32 v[192:193], v[192:193], v[234:235]
	v_pk_add_f32 v[194:195], v[194:195], v[236:237]
	v_pk_add_f32 v[196:197], v[196:197], v[230:231]
	v_pk_add_f32 v[198:199], v[198:199], v[232:233]
	v_pk_add_f32 v[200:201], v[200:201], v[234:235]
	v_pk_add_f32 v[202:203], v[202:203], v[236:237]
	v_pk_add_f32 v[204:205], v[204:205], v[230:231]
	v_pk_add_f32 v[206:207], v[206:207], v[232:233]
	v_pk_add_f32 v[208:209], v[208:209], v[234:235]
	v_pk_add_f32 v[210:211], v[210:211], v[236:237]
	v_pk_add_f32 v[212:213], v[212:213], v[230:231]
	v_pk_add_f32 v[214:215], v[214:215], v[232:233]
	v_pk_add_f32 v[216:217], v[216:217], v[234:235]
	v_pk_add_f32 v[218:219], v[218:219], v[236:237]
	v_pk_add_f32 v[222:223], v[222:223], v[230:231]
	v_pk_add_f32 v[224:225], v[224:225], v[232:233]
	v_pk_add_f32 v[226:227], v[226:227], v[234:235]
	v_pk_add_f32 v[228:229], v[228:229], v[236:237]
.Lp3d_s63:
	s_or_b64 exec, exec, s[58:59]
	v_lshlrev_b32_e32 v230, 16, v96
	v_and_b32_e32 v231, 0xffff0000, v96
	v_lshlrev_b32_e32 v232, 16, v97
	v_and_b32_e32 v233, 0xffff0000, v97
	v_lshlrev_b32_e32 v234, 16, v98
	v_and_b32_e32 v235, 0xffff0000, v98
	v_lshlrev_b32_e32 v236, 16, v99
	v_and_b32_e32 v237, 0xffff0000, v99
	s_and_saveexec_b64 s[58:59], s[22:23]
	s_cbranch_execz .Lp3d_s64
	v_pk_add_f32 v[164:165], v[164:165], v[230:231]
	v_pk_add_f32 v[166:167], v[166:167], v[232:233]
	v_pk_add_f32 v[168:169], v[168:169], v[234:235]
	v_pk_add_f32 v[170:171], v[170:171], v[236:237]
	v_pk_add_f32 v[172:173], v[172:173], v[230:231]
	v_pk_add_f32 v[174:175], v[174:175], v[232:233]
	v_pk_add_f32 v[176:177], v[176:177], v[234:235]
	v_pk_add_f32 v[178:179], v[178:179], v[236:237]
	v_pk_add_f32 v[180:181], v[180:181], v[230:231]
	v_pk_add_f32 v[182:183], v[182:183], v[232:233]
	v_pk_add_f32 v[184:185], v[184:185], v[234:235]
	v_pk_add_f32 v[186:187], v[186:187], v[236:237]
	v_pk_add_f32 v[188:189], v[188:189], v[230:231]
	v_pk_add_f32 v[190:191], v[190:191], v[232:233]
	v_pk_add_f32 v[192:193], v[192:193], v[234:235]
	v_pk_add_f32 v[194:195], v[194:195], v[236:237]
	v_pk_add_f32 v[196:197], v[196:197], v[230:231]
	v_pk_add_f32 v[198:199], v[198:199], v[232:233]
	v_pk_add_f32 v[200:201], v[200:201], v[234:235]
	v_pk_add_f32 v[202:203], v[202:203], v[236:237]
	v_pk_add_f32 v[204:205], v[204:205], v[230:231]
	v_pk_add_f32 v[206:207], v[206:207], v[232:233]
	v_pk_add_f32 v[208:209], v[208:209], v[234:235]
	v_pk_add_f32 v[210:211], v[210:211], v[236:237]
	v_pk_add_f32 v[212:213], v[212:213], v[230:231]
	v_pk_add_f32 v[214:215], v[214:215], v[232:233]
	v_pk_add_f32 v[216:217], v[216:217], v[234:235]
	v_pk_add_f32 v[218:219], v[218:219], v[236:237]
.Lp3d_s64:
	s_or_b64 exec, exec, s[58:59]
	v_lshlrev_b32_e32 v230, 16, v92
	v_and_b32_e32 v231, 0xffff0000, v92
	v_lshlrev_b32_e32 v232, 16, v93
	v_and_b32_e32 v233, 0xffff0000, v93
	v_lshlrev_b32_e32 v234, 16, v94
	v_and_b32_e32 v235, 0xffff0000, v94
	v_lshlrev_b32_e32 v236, 16, v95
	v_and_b32_e32 v237, 0xffff0000, v95
	s_and_saveexec_b64 s[58:59], s[22:23]
	s_cbranch_execz .Lp3d_s65
	v_pk_add_f32 v[164:165], v[164:165], v[230:231]
	v_pk_add_f32 v[166:167], v[166:167], v[232:233]
	v_pk_add_f32 v[168:169], v[168:169], v[234:235]
	v_pk_add_f32 v[170:171], v[170:171], v[236:237]
	v_pk_add_f32 v[172:173], v[172:173], v[230:231]
	v_pk_add_f32 v[174:175], v[174:175], v[232:233]
	v_pk_add_f32 v[176:177], v[176:177], v[234:235]
	v_pk_add_f32 v[178:179], v[178:179], v[236:237]
	v_pk_add_f32 v[180:181], v[180:181], v[230:231]
	v_pk_add_f32 v[182:183], v[182:183], v[232:233]
	v_pk_add_f32 v[184:185], v[184:185], v[234:235]
	v_pk_add_f32 v[186:187], v[186:187], v[236:237]
	v_pk_add_f32 v[188:189], v[188:189], v[230:231]
	v_pk_add_f32 v[190:191], v[190:191], v[232:233]
	v_pk_add_f32 v[192:193], v[192:193], v[234:235]
	v_pk_add_f32 v[194:195], v[194:195], v[236:237]
	v_pk_add_f32 v[196:197], v[196:197], v[230:231]
	v_pk_add_f32 v[198:199], v[198:199], v[232:233]
	v_pk_add_f32 v[200:201], v[200:201], v[234:235]
	v_pk_add_f32 v[202:203], v[202:203], v[236:237]
	v_pk_add_f32 v[204:205], v[204:205], v[230:231]
	v_pk_add_f32 v[206:207], v[206:207], v[232:233]
	v_pk_add_f32 v[208:209], v[208:209], v[234:235]
	v_pk_add_f32 v[210:211], v[210:211], v[236:237]
; __global__ void __launch_bounds__(512, 2) hybrid_fwd(Args args) {
;     ...
;                 for (int j = 0; j < 16; ++j) {
;                     if (j < w && tl - j >= 0) {
;                         const u32x4 v = *(const u32x4*)(xp - (size_t)j * 512);
;                         if (j == 0) x0 = v;
; #pragma unroll
;                         for (int e = 0; e < 4; ++e) { sum[2 * e] += __builtin_bit_cast(float, v[e] << 16); sum[2 * e + 1] += __builtin_bit_cast(float, v[e] & 0xffff0000u); }
;                     }
;                 }
.Lp3d_s65:
	s_or_b64 exec, exec, s[58:59]
	v_lshlrev_b32_e32 v230, 16, v88
	v_and_b32_e32 v231, 0xffff0000, v88
	v_lshlrev_b32_e32 v232, 16, v89
	v_and_b32_e32 v233, 0xffff0000, v89
	v_lshlrev_b32_e32 v234, 16, v90
	v_and_b32_e32 v235, 0xffff0000, v90
	v_lshlrev_b32_e32 v236, 16, v91
	v_and_b32_e32 v237, 0xffff0000, v91
	s_and_saveexec_b64 s[58:59], s[22:23]
	s_cbranch_execz .Lp3d_s66
	v_pk_add_f32 v[164:165], v[164:165], v[230:231]
	v_pk_add_f32 v[166:167], v[166:167], v[232:233]
	v_pk_add_f32 v[168:169], v[168:169], v[234:235]
	v_pk_add_f32 v[170:171], v[170:171], v[236:237]
	v_pk_add_f32 v[172:173], v[172:173], v[230:231]
	v_pk_add_f32 v[174:175], v[174:175], v[232:233]
	v_pk_add_f32 v[176:177], v[176:177], v[234:235]
	v_pk_add_f32 v[178:179], v[178:179], v[236:237]
	v_pk_add_f32 v[180:181], v[180:181], v[230:231]
	v_pk_add_f32 v[182:183], v[182:183], v[232:233]
	v_pk_add_f32 v[184:185], v[184:185], v[234:235]
	v_pk_add_f32 v[186:187], v[186:187], v[236:237]
	v_pk_add_f32 v[188:189], v[188:189], v[230:231]
	v_pk_add_f32 v[190:191], v[190:191], v[232:233]
	v_pk_add_f32 v[192:193], v[192:193], v[234:235]
	v_pk_add_f32 v[194:195], v[194:195], v[236:237]
	v_pk_add_f32 v[196:197], v[196:197], v[230:231]
	v_pk_add_f32 v[198:199], v[198:199], v[232:233]
	v_pk_add_f32 v[200:201], v[200:201], v[234:235]
	v_pk_add_f32 v[202:203], v[202:203], v[236:237]
.Lp3d_s66:
	s_or_b64 exec, exec, s[58:59]
	v_lshlrev_b32_e32 v230, 16, v84
	v_and_b32_e32 v231, 0xffff0000, v84
	v_lshlrev_b32_e32 v232, 16, v85
	v_and_b32_e32 v233, 0xffff0000, v85
	v_lshlrev_b32_e32 v234, 16, v86
	v_and_b32_e32 v235, 0xffff0000, v86
	v_lshlrev_b32_e32 v236, 16, v87
	v_and_b32_e32 v237, 0xffff0000, v87
	s_and_saveexec_b64 s[58:59], s[22:23]
	s_cbranch_execz .Lp3d_s67
	v_pk_add_f32 v[164:165], v[164:165], v[230:231]
	v_pk_add_f32 v[166:167], v[166:167], v[232:233]
	v_pk_add_f32 v[168:169], v[168:169], v[234:235]
	v_pk_add_f32 v[170:171], v[170:171], v[236:237]
	v_pk_add_f32 v[172:173], v[172:173], v[230:231]
	v_pk_add_f32 v[174:175], v[174:175], v[232:233]
	v_pk_add_f32 v[176:177], v[176:177], v[234:235]
	v_pk_add_f32 v[178:179], v[178:179], v[236:237]
	v_pk_add_f32 v[180:181], v[180:181], v[230:231]
	v_pk_add_f32 v[182:183], v[182:183], v[232:233]
	v_pk_add_f32 v[184:185], v[184:185], v[234:235]
	v_pk_add_f32 v[186:187], v[186:187], v[236:237]
	v_pk_add_f32 v[188:189], v[188:189], v[230:231]
	v_pk_add_f32 v[190:191], v[190:191], v[232:233]
	v_pk_add_f32 v[192:193], v[192:193], v[234:235]
	v_pk_add_f32 v[194:195], v[194:195], v[236:237]
.Lp3d_s67:
	s_or_b64 exec, exec, s[58:59]
	v_lshlrev_b32_e32 v230, 16, v80
	v_and_b32_e32 v231, 0xffff0000, v80
	v_lshlrev_b32_e32 v232, 16, v81
	v_and_b32_e32 v233, 0xffff0000, v81
	v_lshlrev_b32_e32 v234, 16, v82
	v_and_b32_e32 v235, 0xffff0000, v82
	v_lshlrev_b32_e32 v236, 16, v83
	v_and_b32_e32 v237, 0xffff0000, v83
	s_and_saveexec_b64 s[58:59], s[22:23]
	s_cbranch_execz .Lp3d_s68
	v_pk_add_f32 v[164:165], v[164:165], v[230:231]
	v_pk_add_f32 v[166:167], v[166:167], v[232:233]
	v_pk_add_f32 v[168:169], v[168:169], v[234:235]
	v_pk_add_f32 v[170:171], v[170:171], v[236:237]
	v_pk_add_f32 v[172:173], v[172:173], v[230:231]
	v_pk_add_f32 v[174:175], v[174:175], v[232:233]
	v_pk_add_f32 v[176:177], v[176:177], v[234:235]
	v_pk_add_f32 v[178:179], v[178:179], v[236:237]
	v_pk_add_f32 v[180:181], v[180:181], v[230:231]
	v_pk_add_f32 v[182:183], v[182:183], v[232:233]
	v_pk_add_f32 v[184:185], v[184:185], v[234:235]
	v_pk_add_f32 v[186:187], v[186:187], v[236:237]
.Lp3d_s68:
	s_or_b64 exec, exec, s[58:59]
	v_lshlrev_b32_e32 v230, 16, v76
	v_and_b32_e32 v231, 0xffff0000, v76
	v_lshlrev_b32_e32 v232, 16, v77
	v_and_b32_e32 v233, 0xffff0000, v77
	v_lshlrev_b32_e32 v234, 16, v78
	v_and_b32_e32 v235, 0xffff0000, v78
	v_lshlrev_b32_e32 v236, 16, v79
	v_and_b32_e32 v237, 0xffff0000, v79
	s_and_saveexec_b64 s[58:59], s[22:23]
	s_cbranch_execz .Lp3d_s69
	v_pk_add_f32 v[164:165], v[164:165], v[230:231]
	v_pk_add_f32 v[166:167], v[166:167], v[232:233]
	v_pk_add_f32 v[168:169], v[168:169], v[234:235]
	v_pk_add_f32 v[170:171], v[170:171], v[236:237]
	v_pk_add_f32 v[172:173], v[172:173], v[230:231]
	v_pk_add_f32 v[174:175], v[174:175], v[232:233]
	v_pk_add_f32 v[176:177], v[176:177], v[234:235]
	v_pk_add_f32 v[178:179], v[178:179], v[236:237]
.Lp3d_s69:
	s_or_b64 exec, exec, s[58:59]
	v_lshlrev_b32_e32 v230, 16, v72
	v_and_b32_e32 v231, 0xffff0000, v72
	v_lshlrev_b32_e32 v232, 16, v73
	v_and_b32_e32 v233, 0xffff0000, v73
	v_lshlrev_b32_e32 v234, 16, v74
	v_and_b32_e32 v235, 0xffff0000, v74
	v_lshlrev_b32_e32 v236, 16, v75
	v_and_b32_e32 v237, 0xffff0000, v75
	s_and_saveexec_b64 s[58:59], s[22:23]
	s_cbranch_execz .Lp3d_s70
	v_pk_add_f32 v[164:165], v[164:165], v[230:231]
	v_pk_add_f32 v[166:167], v[166:167], v[232:233]
	v_pk_add_f32 v[168:169], v[168:169], v[234:235]
	v_pk_add_f32 v[170:171], v[170:171], v[236:237]
; __device__ __forceinline__ unsigned cvt_pk_bf16(float lo, float hi) { f32x2_t v = {lo, hi}; bf16x2_t b = __builtin_convertvector(v, bf16x2_t); return __builtin_bit_cast(unsigned, b); }
; __global__ void __launch_bounds__(512, 2) hybrid_fwd(Args args) {
;     ...
;                 const float inv = 1.0f / (float)(tl + 1 < w ? tl + 1 : w);
;                 float p[8];
; #pragma unroll
;                 for (int e = 0; e < 4; ++e) { p[2 * e] = sum[2 * e] * inv - __builtin_bit_cast(float, x0[e] << 16); p[2 * e + 1] = sum[2 * e + 1] * inv - __builtin_bit_cast(float, x0[e] & 0xffff0000u); }
;                 u32x4 o; o.x = cvt_pk_bf16(p[0], p[1]); o.y = cvt_pk_bf16(p[2], p[3]); o.z = cvt_pk_bf16(p[4], p[5]); o.w = cvt_pk_bf16(p[6], p[7]);
;                 *(u32x4*)(POOLED + (size_t)t * 512 + cg8 * 8) = o;
.Lp3d_s70:
	s_or_b64 exec, exec, s[58:59]
	v_add_u32_e32 v12, 9, v31
	v_min_i32_e32 v12, v12, v28
	v_cvt_f32_i32_e32 v13, v12
	v_div_scale_f32 v24, s[58:59], v13, v13, 1.0
	v_rcp_f32_e32 v25, v24
	v_div_scale_f32 v14, vcc, 1.0, v13, 1.0
	v_fma_f32 v15, -v24, v25, 1.0
	v_fmac_f32_e32 v25, v15, v25
	v_mul_f32_e32 v15, v14, v25
	v_fma_f32 v16, -v24, v15, v14
	v_fmac_f32_e32 v15, v16, v25
	v_fma_f32 v24, -v24, v15, v14
	v_div_fmas_f32 v24, v24, v25, v15
	v_div_fixup_f32 v24, v24, v13, 1.0
	v_lshlrev_b32_e32 v230, 16, v132
	v_and_b32_e32 v231, 0xffff0000, v132
	v_lshlrev_b32_e32 v232, 16, v133
	v_and_b32_e32 v233, 0xffff0000, v133
	v_lshlrev_b32_e32 v234, 16, v134
	v_and_b32_e32 v235, 0xffff0000, v134
	v_lshlrev_b32_e32 v236, 16, v135
	v_and_b32_e32 v237, 0xffff0000, v135
	v_pk_fma_f32 v[164:165], v[24:25], v[164:165], v[230:231] op_sel_hi:[0,1,1] neg_lo:[0,0,1] neg_hi:[0,0,1]
	v_pk_fma_f32 v[166:167], v[24:25], v[166:167], v[232:233] op_sel_hi:[0,1,1] neg_lo:[0,0,1] neg_hi:[0,0,1]
	v_pk_fma_f32 v[168:169], v[24:25], v[168:169], v[234:235] op_sel_hi:[0,1,1] neg_lo:[0,0,1] neg_hi:[0,0,1]
	v_pk_fma_f32 v[170:171], v[24:25], v[170:171], v[236:237] op_sel_hi:[0,1,1] neg_lo:[0,0,1] neg_hi:[0,0,1]
	v_cvt_pk_bf16_f32 v0, v164, v165
	v_cvt_pk_bf16_f32 v1, v166, v167
	v_cvt_pk_bf16_f32 v2, v168, v169
	v_cvt_pk_bf16_f32 v3, v170, v171
	v_add_co_u32_e32 v240, vcc, 0x2000, v238
	s_nop 1
	v_addc_co_u32_e32 v241, vcc, 0, v239, vcc
	global_store_dwordx4 v[240:241], v[0:3], off
	v_add_u32_e32 v12, 10, v31
	v_min_i32_e32 v12, v12, v28
	v_cvt_f32_i32_e32 v13, v12
	v_div_scale_f32 v24, s[58:59], v13, v13, 1.0
	v_rcp_f32_e32 v25, v24
	v_div_scale_f32 v14, vcc, 1.0, v13, 1.0
	v_fma_f32 v15, -v24, v25, 1.0
	v_fmac_f32_e32 v25, v15, v25
	v_mul_f32_e32 v15, v14, v25
	v_fma_f32 v16, -v24, v15, v14
	v_fmac_f32_e32 v15, v16, v25
	v_fma_f32 v24, -v24, v15, v14
	v_div_fmas_f32 v24, v24, v25, v15
	v_div_fixup_f32 v24, v24, v13, 1.0
	v_lshlrev_b32_e32 v230, 16, v136
	v_and_b32_e32 v231, 0xffff0000, v136
	v_lshlrev_b32_e32 v232, 16, v137
	v_and_b32_e32 v233, 0xffff0000, v137
	v_lshlrev_b32_e32 v234, 16, v138
	v_and_b32_e32 v235, 0xffff0000, v138
	v_lshlrev_b32_e32 v236, 16, v139
	v_and_b32_e32 v237, 0xffff0000, v139
	v_pk_fma_f32 v[172:173], v[24:25], v[172:173], v[230:231] op_sel_hi:[0,1,1] neg_lo:[0,0,1] neg_hi:[0,0,1]
	v_pk_fma_f32 v[174:175], v[24:25], v[174:175], v[232:233] op_sel_hi:[0,1,1] neg_lo:[0,0,1] neg_hi:[0,0,1]
	v_pk_fma_f32 v[176:177], v[24:25], v[176:177], v[234:235] op_sel_hi:[0,1,1] neg_lo:[0,0,1] neg_hi:[0,0,1]
	v_pk_fma_f32 v[178:179], v[24:25], v[178:179], v[236:237] op_sel_hi:[0,1,1] neg_lo:[0,0,1] neg_hi:[0,0,1]
	v_cvt_pk_bf16_f32 v0, v172, v173
	v_cvt_pk_bf16_f32 v1, v174, v175
	v_cvt_pk_bf16_f32 v2, v176, v177
	v_cvt_pk_bf16_f32 v3, v178, v179
	global_store_dwordx4 v[240:241], v[0:3], off offset:1024
	v_add_u32_e32 v12, 11, v31
	v_min_i32_e32 v12, v12, v28
	v_cvt_f32_i32_e32 v13, v12
	v_div_scale_f32 v24, s[58:59], v13, v13, 1.0
	v_rcp_f32_e32 v25, v24
	v_div_scale_f32 v14, vcc, 1.0, v13, 1.0
	v_fma_f32 v15, -v24, v25, 1.0
	v_fmac_f32_e32 v25, v15, v25
	v_mul_f32_e32 v15, v14, v25
	v_fma_f32 v16, -v24, v15, v14
	v_fmac_f32_e32 v15, v16, v25
	v_fma_f32 v24, -v24, v15, v14
	v_div_fmas_f32 v24, v24, v25, v15
	v_div_fixup_f32 v24, v24, v13, 1.0
	v_lshlrev_b32_e32 v230, 16, v140
	v_and_b32_e32 v231, 0xffff0000, v140
	v_lshlrev_b32_e32 v232, 16, v141
	v_and_b32_e32 v233, 0xffff0000, v141
	v_lshlrev_b32_e32 v234, 16, v142
	v_and_b32_e32 v235, 0xffff0000, v142
	v_lshlrev_b32_e32 v236, 16, v143
	v_and_b32_e32 v237, 0xffff0000, v143
	v_pk_fma_f32 v[180:181], v[24:25], v[180:181], v[230:231] op_sel_hi:[0,1,1] neg_lo:[0,0,1] neg_hi:[0,0,1]
	v_pk_fma_f32 v[182:183], v[24:25], v[182:183], v[232:233] op_sel_hi:[0,1,1] neg_lo:[0,0,1] neg_hi:[0,0,1]
	v_pk_fma_f32 v[184:185], v[24:25], v[184:185], v[234:235] op_sel_hi:[0,1,1] neg_lo:[0,0,1] neg_hi:[0,0,1]
	v_pk_fma_f32 v[186:187], v[24:25], v[186:187], v[236:237] op_sel_hi:[0,1,1] neg_lo:[0,0,1] neg_hi:[0,0,1]
	v_cvt_pk_bf16_f32 v0, v180, v181
	v_cvt_pk_bf16_f32 v1, v182, v183
	v_cvt_pk_bf16_f32 v2, v184, v185
	v_cvt_pk_bf16_f32 v3, v186, v187
	global_store_dwordx4 v[240:241], v[0:3], off offset:2048
	v_add_u32_e32 v12, 12, v31
	v_min_i32_e32 v12, v12, v28
	v_cvt_f32_i32_e32 v13, v12
	v_div_scale_f32 v24, s[58:59], v13, v13, 1.0
	v_rcp_f32_e32 v25, v24
	v_div_scale_f32 v14, vcc, 1.0, v13, 1.0
	v_fma_f32 v15, -v24, v25, 1.0
	v_fmac_f32_e32 v25, v15, v25
	v_mul_f32_e32 v15, v14, v25
	v_fma_f32 v16, -v24, v15, v14
	v_fmac_f32_e32 v15, v16, v25
	v_fma_f32 v24, -v24, v15, v14
	v_div_fmas_f32 v24, v24, v25, v15
	v_div_fixup_f32 v24, v24, v13, 1.0
	v_lshlrev_b32_e32 v230, 16, v144
	v_and_b32_e32 v231, 0xffff0000, v144
	v_lshlrev_b32_e32 v232, 16, v145
	v_and_b32_e32 v233, 0xffff0000, v145
	v_lshlrev_b32_e32 v234, 16, v146
	v_and_b32_e32 v235, 0xffff0000, v146
	v_lshlrev_b32_e32 v236, 16, v147
	v_and_b32_e32 v237, 0xffff0000, v147
	v_pk_fma_f32 v[188:189], v[24:25], v[188:189], v[230:231] op_sel_hi:[0,1,1] neg_lo:[0,0,1] neg_hi:[0,0,1]
	v_pk_fma_f32 v[190:191], v[24:25], v[190:191], v[232:233] op_sel_hi:[0,1,1] neg_lo:[0,0,1] neg_hi:[0,0,1]
	v_pk_fma_f32 v[192:193], v[24:25], v[192:193], v[234:235] op_sel_hi:[0,1,1] neg_lo:[0,0,1] neg_hi:[0,0,1]
	v_pk_fma_f32 v[194:195], v[24:25], v[194:195], v[236:237] op_sel_hi:[0,1,1] neg_lo:[0,0,1] neg_hi:[0,0,1]
	v_cvt_pk_bf16_f32 v0, v188, v189
	v_cvt_pk_bf16_f32 v1, v190, v191
	v_cvt_pk_bf16_f32 v2, v192, v193
	v_cvt_pk_bf16_f32 v3, v194, v195
	global_store_dwordx4 v[240:241], v[0:3], off offset:3072
; __device__ __forceinline__ unsigned cvt_pk_bf16(float lo, float hi) { f32x2_t v = {lo, hi}; bf16x2_t b = __builtin_convertvector(v, bf16x2_t); return __builtin_bit_cast(unsigned, b); }
; __global__ void __launch_bounds__(512, 2) hybrid_fwd(Args args) {
;     ...
;                 const float inv = 1.0f / (float)(tl + 1 < w ? tl + 1 : w);
;                 float p[8];
; #pragma unroll
;                 for (int e = 0; e < 4; ++e) { p[2 * e] = sum[2 * e] * inv - __builtin_bit_cast(float, x0[e] << 16); p[2 * e + 1] = sum[2 * e + 1] * inv - __builtin_bit_cast(float, x0[e] & 0xffff0000u); }
;                 u32x4 o; o.x = cvt_pk_bf16(p[0], p[1]); o.y = cvt_pk_bf16(p[2], p[3]); o.z = cvt_pk_bf16(p[4], p[5]); o.w = cvt_pk_bf16(p[6], p[7]);
;                 *(u32x4*)(POOLED + (size_t)t * 512 + cg8 * 8) = o;
;             }
	v_add_u32_e32 v12, 13, v31
	v_min_i32_e32 v12, v12, v28
	v_cvt_f32_i32_e32 v13, v12
	v_div_scale_f32 v24, s[58:59], v13, v13, 1.0
	v_rcp_f32_e32 v25, v24
	v_div_scale_f32 v14, vcc, 1.0, v13, 1.0
	v_fma_f32 v15, -v24, v25, 1.0
	v_fmac_f32_e32 v25, v15, v25
	v_mul_f32_e32 v15, v14, v25
	v_fma_f32 v16, -v24, v15, v14
	v_fmac_f32_e32 v15, v16, v25
	v_fma_f32 v24, -v24, v15, v14
	v_div_fmas_f32 v24, v24, v25, v15
	v_div_fixup_f32 v24, v24, v13, 1.0
	v_lshlrev_b32_e32 v230, 16, v148
	v_and_b32_e32 v231, 0xffff0000, v148
	v_lshlrev_b32_e32 v232, 16, v149
	v_and_b32_e32 v233, 0xffff0000, v149
	v_lshlrev_b32_e32 v234, 16, v150
	v_and_b32_e32 v235, 0xffff0000, v150
	v_lshlrev_b32_e32 v236, 16, v151
	v_and_b32_e32 v237, 0xffff0000, v151
	v_pk_fma_f32 v[196:197], v[24:25], v[196:197], v[230:231] op_sel_hi:[0,1,1] neg_lo:[0,0,1] neg_hi:[0,0,1]
	v_pk_fma_f32 v[198:199], v[24:25], v[198:199], v[232:233] op_sel_hi:[0,1,1] neg_lo:[0,0,1] neg_hi:[0,0,1]
	v_pk_fma_f32 v[200:201], v[24:25], v[200:201], v[234:235] op_sel_hi:[0,1,1] neg_lo:[0,0,1] neg_hi:[0,0,1]
	v_pk_fma_f32 v[202:203], v[24:25], v[202:203], v[236:237] op_sel_hi:[0,1,1] neg_lo:[0,0,1] neg_hi:[0,0,1]
	v_cvt_pk_bf16_f32 v0, v196, v197
	v_cvt_pk_bf16_f32 v1, v198, v199
	v_cvt_pk_bf16_f32 v2, v200, v201
	v_cvt_pk_bf16_f32 v3, v202, v203
	v_add_co_u32_e32 v240, vcc, 0x3000, v238
	s_nop 1
	v_addc_co_u32_e32 v241, vcc, 0, v239, vcc
	global_store_dwordx4 v[240:241], v[0:3], off
	v_add_u32_e32 v12, 14, v31
	v_min_i32_e32 v12, v12, v28
	v_cvt_f32_i32_e32 v13, v12
	v_div_scale_f32 v24, s[58:59], v13, v13, 1.0
	v_rcp_f32_e32 v25, v24
	v_div_scale_f32 v14, vcc, 1.0, v13, 1.0
	v_fma_f32 v15, -v24, v25, 1.0
	v_fmac_f32_e32 v25, v15, v25
	v_mul_f32_e32 v15, v14, v25
	v_fma_f32 v16, -v24, v15, v14
	v_fmac_f32_e32 v15, v16, v25
	v_fma_f32 v24, -v24, v15, v14
	v_div_fmas_f32 v24, v24, v25, v15
	v_div_fixup_f32 v24, v24, v13, 1.0
	v_lshlrev_b32_e32 v230, 16, v152
	v_and_b32_e32 v231, 0xffff0000, v152
	v_lshlrev_b32_e32 v232, 16, v153
	v_and_b32_e32 v233, 0xffff0000, v153
	v_lshlrev_b32_e32 v234, 16, v154
	v_and_b32_e32 v235, 0xffff0000, v154
	v_lshlrev_b32_e32 v236, 16, v155
	v_and_b32_e32 v237, 0xffff0000, v155
	v_pk_fma_f32 v[204:205], v[24:25], v[204:205], v[230:231] op_sel_hi:[0,1,1] neg_lo:[0,0,1] neg_hi:[0,0,1]
	v_pk_fma_f32 v[206:207], v[24:25], v[206:207], v[232:233] op_sel_hi:[0,1,1] neg_lo:[0,0,1] neg_hi:[0,0,1]
	v_pk_fma_f32 v[208:209], v[24:25], v[208:209], v[234:235] op_sel_hi:[0,1,1] neg_lo:[0,0,1] neg_hi:[0,0,1]
	v_pk_fma_f32 v[210:211], v[24:25], v[210:211], v[236:237] op_sel_hi:[0,1,1] neg_lo:[0,0,1] neg_hi:[0,0,1]
	v_cvt_pk_bf16_f32 v0, v204, v205
	v_cvt_pk_bf16_f32 v1, v206, v207
	v_cvt_pk_bf16_f32 v2, v208, v209
	v_cvt_pk_bf16_f32 v3, v210, v211
	global_store_dwordx4 v[240:241], v[0:3], off offset:1024
	v_add_u32_e32 v12, 15, v31
	v_min_i32_e32 v12, v12, v28
	v_cvt_f32_i32_e32 v13, v12
	v_div_scale_f32 v24, s[58:59], v13, v13, 1.0
	v_rcp_f32_e32 v25, v24
	v_div_scale_f32 v14, vcc, 1.0, v13, 1.0
	v_fma_f32 v15, -v24, v25, 1.0
	v_fmac_f32_e32 v25, v15, v25
	v_mul_f32_e32 v15, v14, v25
	v_fma_f32 v16, -v24, v15, v14
	v_fmac_f32_e32 v15, v16, v25
	v_fma_f32 v24, -v24, v15, v14
	v_div_fmas_f32 v24, v24, v25, v15
	v_div_fixup_f32 v24, v24, v13, 1.0
	v_lshlrev_b32_e32 v230, 16, v156
	v_and_b32_e32 v231, 0xffff0000, v156
	v_lshlrev_b32_e32 v232, 16, v157
	v_and_b32_e32 v233, 0xffff0000, v157
	v_lshlrev_b32_e32 v234, 16, v158
	v_and_b32_e32 v235, 0xffff0000, v158
	v_lshlrev_b32_e32 v236, 16, v159
	v_and_b32_e32 v237, 0xffff0000, v159
	v_pk_fma_f32 v[212:213], v[24:25], v[212:213], v[230:231] op_sel_hi:[0,1,1] neg_lo:[0,0,1] neg_hi:[0,0,1]
	v_pk_fma_f32 v[214:215], v[24:25], v[214:215], v[232:233] op_sel_hi:[0,1,1] neg_lo:[0,0,1] neg_hi:[0,0,1]
	v_pk_fma_f32 v[216:217], v[24:25], v[216:217], v[234:235] op_sel_hi:[0,1,1] neg_lo:[0,0,1] neg_hi:[0,0,1]
	v_pk_fma_f32 v[218:219], v[24:25], v[218:219], v[236:237] op_sel_hi:[0,1,1] neg_lo:[0,0,1] neg_hi:[0,0,1]
	v_cvt_pk_bf16_f32 v0, v212, v213
	v_cvt_pk_bf16_f32 v1, v214, v215
	v_cvt_pk_bf16_f32 v2, v216, v217
	v_cvt_pk_bf16_f32 v3, v218, v219
	global_store_dwordx4 v[240:241], v[0:3], off offset:2048
	v_add_u32_e32 v12, 16, v31
	v_min_i32_e32 v12, v12, v28
	v_cvt_f32_i32_e32 v13, v12
	v_div_scale_f32 v24, s[58:59], v13, v13, 1.0
	v_rcp_f32_e32 v25, v24
	v_div_scale_f32 v14, vcc, 1.0, v13, 1.0
	v_fma_f32 v15, -v24, v25, 1.0
	v_fmac_f32_e32 v25, v15, v25
	v_mul_f32_e32 v15, v14, v25
	v_fma_f32 v16, -v24, v15, v14
	v_fmac_f32_e32 v15, v16, v25
	v_fma_f32 v24, -v24, v15, v14
	v_div_fmas_f32 v24, v24, v25, v15
	v_div_fixup_f32 v24, v24, v13, 1.0
	v_lshlrev_b32_e32 v230, 16, v160
	v_and_b32_e32 v231, 0xffff0000, v160
	v_lshlrev_b32_e32 v232, 16, v161
	v_and_b32_e32 v233, 0xffff0000, v161
	v_lshlrev_b32_e32 v234, 16, v162
	v_and_b32_e32 v235, 0xffff0000, v162
	v_lshlrev_b32_e32 v236, 16, v163
	v_and_b32_e32 v237, 0xffff0000, v163
	v_pk_fma_f32 v[222:223], v[24:25], v[222:223], v[230:231] op_sel_hi:[0,1,1] neg_lo:[0,0,1] neg_hi:[0,0,1]
	v_pk_fma_f32 v[224:225], v[24:25], v[224:225], v[232:233] op_sel_hi:[0,1,1] neg_lo:[0,0,1] neg_hi:[0,0,1]
	v_pk_fma_f32 v[226:227], v[24:25], v[226:227], v[234:235] op_sel_hi:[0,1,1] neg_lo:[0,0,1] neg_hi:[0,0,1]
	v_pk_fma_f32 v[228:229], v[24:25], v[228:229], v[236:237] op_sel_hi:[0,1,1] neg_lo:[0,0,1] neg_hi:[0,0,1]
	v_cvt_pk_bf16_f32 v0, v222, v223
	v_cvt_pk_bf16_f32 v1, v224, v225
	v_cvt_pk_bf16_f32 v2, v226, v227
	v_cvt_pk_bf16_f32 v3, v228, v229
	global_store_dwordx4 v[240:241], v[0:3], off offset:3072
	s_branch .LBB0_359
